# MLA loop: 3-deep K-fragment LDS prefetch, half-iteration stagger of waves 4-7 with triple-buffered V, softmax scale folded into q (MFMA C-init = -max) removing 33 VALU per tile
# speedup vs baseline: 1.0214x; 1.0214x over previous
; #define LAS __attribute__((address_space(3)))
; __global__ void __launch_bounds__(NTHR) mega(Params p) {
;   extern __shared__ __attribute__((aligned(16))) char lds[];
;   cg::grid_group grid = cg::this_grid();
;   volatile LAS unsigned* bst = (volatile LAS unsigned*)(lds + 151552);
;   if (threadIdx.x == 0) { bst[0] = 0u; bst[1] = 0u; }
;   __syncthreads();
;   const XcdBarrier xb = xcd_barrier_post((unsigned*)(p.ws + O_BAR), bst);
_Z4mega6Params:
	s_load_dwordx4 s[64:67], s[0:1], 0xc0
	s_load_dword s72, s[0:1], 0xd0
	v_and_b32_e32 v204, 0x3ff, v0
	v_readfirstlane_b32 s100, v0
	s_nop 3
	s_and_b32 s100, s100, 0x3ff
	s_lshr_b32 s100, s100, 8
	s_mov_b32 s58, s2
	v_cmp_ne_u32_e64 s[2:3], 0, v204
	s_add_u32 s8, s0, 0xc8
	s_addc_u32 s9, s1, 0
	v_writelane_b32 v249, s2, 0
	v_cmp_eq_u32_e64 s[6:7], 0, v204
	s_nop 0
	v_writelane_b32 v249, s3, 1
	s_mov_b64 s[2:3], exec
	v_writelane_b32 v249, s6, 2
	s_nop 1
	v_writelane_b32 v249, s7, 3
	s_and_b64 s[6:7], s[2:3], s[6:7]
	s_mov_b64 exec, s[6:7]
	s_cbranch_execz .LBB0_2
	s_add_i32 s6, 0, 0x25000
	v_mov_b32_e32 v1, 0
	v_mov_b32_e32 v2, s6
	s_add_i32 s6, 0, 0x25004
	ds_write_b32 v2, v1
	v_mov_b32_e32 v2, s6
	ds_write_b32 v2, v1

; DEV int ltid() { int t = threadIdx.x; asm volatile("" : "+v"(t)); return t; }
; DEV int v_st(int k, int c) { const int kk = (k & ~0xC) | ((k & 4) << 1) | ((k & 8) >> 1); return ((kk >> 3) * 4 + (c >> 5)) * 512 + ((kk & 7) * 32 + (c & 31)) * 2; }
; DEV int v_rd_base(int lane) { return ((lane & 3) << 3) | (((lane >> 2) & 3) << 6) | (((lane >> 4) & 1) << 5) | (((lane >> 5) & 1) << 8); }
; template <int DQK, bool WIN, bool TWO>
; DEV void attn_unit(const bf16_t* Qb, int ldq, const bf16_t* __restrict__ Kh, int ldk, const bf16_t* __restrict__ Vh, int ldv,
;                    bf16_t* Ob, int ldo, int kbeg, int NT, int q0, float sink, const float SCALE, char* lds) {
;   using CF = ACfg<DQK>;
;   constexpr int KROW = CF::KROW, KT = CF::KT, NKP = CF::NKP, PPR = CF::PPR, SHM_V = 16384;
;   const float C = SCALE * 1.4426950408889634f, thr_raw = 8.f / SCALE;
;   const int tid = ltid(), wid = tid >> 6, lane = tid & 63, r32 = lane & 31, hi = lane >> 5;
;   char* V_lds = lds; char* K_lds = lds + 2 * SHM_V;
;   float* wsf = (float*)(lds + 2 * SHM_V + 2 * KT) + wid * 64; float* li_l = wsf; float* al_l = wsf + 32;
;   float m_reg = -1e30f, l_reg = 0;
;   f32x16 o[4];
; #pragma unroll
;   for (int d = 0; d < 4; ++d)
; #pragma unroll
;     for (int r = 0; r < 16; ++r) o[d][r] = 0.f;
;   constexpr int NQR = TWO ? 4 : DQK / 16;
;   bf16x8 qr[NQR];
;   const bf16_t* Qw = Qb + (size_t)(wid * 32 + r32) * ldq + hi * 8;
;   char* qlds = lds + 2 * SHM_V + 2 * KT + 2048 + wid * 8192 + lane * 16;
; #pragma unroll
;   for (int d0 = 0; d0 < NQR; ++d0) qr[d0] = *(const bf16x8*)(Qw + d0 * 16);
; #pragma unroll
;   for (int d0 = NQR; d0 < DQK / 16; ++d0) *(bf16x8*)(qlds + (d0 - NQR) * 1024) = *(const bf16x8*)(Qw + d0 * 16);
;   const int sr = tid >> 4, sc = (tid & 15) * 8, vst0 = v_st(sr, sc), vst1 = v_st(32 + sr, sc);
;   const int vb0 = (int)(uintptr_t)V_lds + v_rd_base(lane);
;   const unsigned voff = (unsigned)(sr * ldv + sc) * 2u, vstep = (unsigned)ldv * 64u;
;   unsigned koff[NKP]; int klds[NKP];
; #pragma unroll
;   for (int i = 0; i < NKP; ++i) { const int p = tid + i * NTHR; const int kr = p / PPR, kc = (p % PPR) * 8; koff[i] = (unsigned)(kr * ldk + kc) * 2u; klds[i] = kr * KROW + kc * 2; }
;   const int qpos = q0 + wid * 32 + r32;
;   bf16x8 svs0, svs1, sks[NKP];
.LBB0_460:
	s_and_b32 s0, s21, 7
	s_bfe_u32 s1, s26, 0x50003
	v_readlane_b32 s2, v252, 46
	s_mul_i32 s35, s0, 0x180
	s_lshl_b32 s34, s0, 8
	s_ashr_i32 s0, s26, 8
	s_and_b32 s18, s1, s2
	v_readlane_b32 s2, v253, 50
	s_lshr_b32 s1, s1, s51
	s_lshl_b32 s0, s0, s2
	s_add_i32 s0, s1, s0
	s_ashr_i32 s1, s0, 31
	v_readlane_b32 s2, v249, 0
	s_and_b32 s24, s26, 7
	s_lshl_b64 s[2:3], s[0:1], s2
	s_lshl_b32 s0, s18, 8
	s_add_u32 s0, s2, s0
	s_addc_u32 s1, s3, 0
	s_mul_i32 s18, s1, 0xc00
	s_mul_hi_u32 s19, s0, 0xc00
	s_add_i32 s19, s19, s18
	s_mul_i32 s18, s0, 0xc00
	s_add_u32 s18, s78, s18
	s_addc_u32 s19, s79, s19
	s_mul_i32 s25, s24, 0x180
	s_add_u32 s38, s18, s25
	s_mul_i32 s18, s3, 0xc00
	s_mul_hi_u32 s40, s2, 0xc00
	s_addc_u32 s39, s19, 0
	s_add_i32 s40, s40, s18
	s_mul_i32 s41, s2, 0xc00
	v_readlane_b32 s4, v250, 0
	v_readlane_b32 s5, v250, 1
	s_add_u32 s18, s4, s41
	s_addc_u32 s19, s5, s40
	s_add_u32 s18, s18, s25
	s_addc_u32 s19, s19, 0
	s_lshl_b64 s[2:3], s[2:3], 11
	v_readlane_b32 s4, v249, 6
	v_readlane_b32 s5, v249, 7
	s_add_u32 s25, s4, s2
	s_addc_u32 s42, s5, s3
	s_lshl_b32 s27, s24, 7
	s_lshl_b32 s24, s24, 8
	v_mov_b32_e32 v2, v204
	s_add_u32 s24, s25, s24
	s_addc_u32 s25, s42, 0
	v_ashrrev_i32_e32 v3, 6, v2
	v_and_b32_e32 v175, 31, v2
	v_and_b32_e32 v0, 0x3fffffc0, v2
	s_add_i32 s42, 0, 0x14800
	v_lshlrev_b32_e32 v174, 5, v3
	v_lshl_add_u32 v173, v0, 2, s42
	v_bfe_u32 v172, v2, 5, 1
	v_or_b32_e32 v4, v174, v175
	v_mov_b64_e32 v[0:1], s[38:39]
	s_movk_i32 s4, 0xc00
	v_mad_i64_i32 v[0:1], s[38:39], v4, s4, v[0:1]
	v_lshlrev_b32_e32 v196, 4, v172
	v_lshl_add_u64 v[0:1], v[0:1], 0, v[196:197]
	global_load_dwordx4 v[140:143], v[0:1], off
	global_load_dwordx4 v[136:139], v[0:1], off offset:32
	global_load_dwordx4 v[132:135], v[0:1], off offset:64
	global_load_dwordx4 v[128:131], v[0:1], off offset:96
	global_load_dwordx4 v[124:127], v[0:1], off offset:128
	global_load_dwordx4 v[120:123], v[0:1], off offset:160
	global_load_dwordx4 v[116:119], v[0:1], off offset:192
	global_load_dwordx4 v[112:115], v[0:1], off offset:224
	global_load_dwordx4 v[108:111], v[0:1], off offset:256
	global_load_dwordx4 v[104:107], v[0:1], off offset:288
	global_load_dwordx4 v[100:103], v[0:1], off offset:320
	global_load_dwordx4 v[96:99], v[0:1], off offset:352
	v_ashrrev_i32_e32 v0, 4, v2
	v_lshlrev_b32_e32 v31, 13, v3
	v_and_b32_e32 v3, 0xfffff0, v0
	v_lshlrev_b32_e32 v4, 1, v0
	v_and_or_b32 v3, v4, 8, v3
	v_lshrrev_b32_e32 v4, 1, v0
	v_and_b32_e32 v6, 3, v0
	v_and_or_b32 v4, v4, 4, v6
	v_lshlrev_b32_e32 v38, 6, v4
	v_add_u32_e32 v4, 32, v0
	v_and_b32_e32 v6, 0xfffff0, v4
	v_lshlrev_b32_e32 v4, 1, v4
	v_lshlrev_b32_e32 v33, 3, v2
	v_and_or_b32 v4, v4, 8, v6
	v_bfe_u32 v5, v33, 5, 2
	v_lshrrev_b32_e32 v4, 1, v4
	v_or_b32_e32 v4, v4, v5
	s_mov_b32 s5, 0x2aaaaaab
	v_lshrrev_b32_e32 v3, 1, v3
	v_lshlrev_b32_e32 v39, 9, v4
	v_mul_hi_i32 v4, v2, s5
	v_or_b32_e32 v3, v3, v5
	v_lshrrev_b32_e32 v5, 31, v4
	v_ashrrev_i32_e32 v4, 2, v4
	v_add_u32_e32 v4, v4, v5
	v_mul_lo_u32 v5, v4, 24
	v_sub_u32_e32 v5, v2, v5
	v_mul_lo_u32 v6, v4, s4
	v_lshl_add_u32 v16, v5, 4, v6
	s_movk_i32 s39, 0xf590
	v_mad_u64_u32 v[20:21], s[42:43], v4, s39, v[16:17]
	v_add_u32_e32 v4, 0x200, v2
	v_mul_hi_i32 v5, v4, s5
	v_lshrrev_b32_e32 v6, 31, v5
	v_ashrrev_i32_e32 v5, 2, v5
	v_add_u32_e32 v5, v5, v6
	v_mul_lo_u32 v6, v5, 24
	v_and_b32_e32 v30, 63, v2
	v_lshlrev_b32_e32 v40, 1, v2
	v_sub_u32_e32 v4, v4, v6
	v_mul_lo_u32 v6, v5, s4
	v_add_u32_e32 v2, 0x400, v2
	s_waitcnt lgkmcnt(0)
	v_lshl_add_u32 v18, v4, 4, v6
	v_mul_hi_i32 v4, v2, s5
	v_mad_u64_u32 v[24:25], s[42:43], v5, s39, v[18:19]
	v_lshrrev_b32_e32 v5, 31, v4
	v_ashrrev_i32_e32 v4, 2, v4
	v_and_b32_e32 v1, 0x78, v33
	v_add_u32_e32 v4, v4, v5
	v_lshlrev_b32_e32 v1, 1, v1
	v_mul_lo_u32 v5, v4, 24
	v_lshlrev_b32_e32 v3, 9, v3
	v_sub_u32_e32 v2, v2, v5
	v_mul_lo_u32 v5, v4, s4
	v_and_b32_e32 v21, 48, v1
	v_lshl_or_b32 v28, v0, 11, v1
	v_lshl_add_u32 v22, v2, 4, v5
	v_or3_b32 v25, v3, v38, v21
	global_load_dwordx4 v[0:3], v28, s[24:25]
	global_load_dwordx4 v[34:37], v22, s[18:19]
	v_mov_b32_e32 v29, v197
	v_mad_u64_u32 v[26:27], s[42:43], v4, s39, v[22:23]
	v_lshl_add_u64 v[4:5], s[24:25], 0, v[28:29]
	s_mov_b32 s4, 0x10000
	v_add_co_u32_e32 v4, vcc, s4, v4
	global_load_dwordx4 v[8:11], v16, s[18:19]
	global_load_dwordx4 v[12:15], v18, s[18:19]
	v_addc_co_u32_e32 v5, vcc, 0, v5, vcc
	global_load_dwordx4 v[4:7], v[4:5], off
	v_add_u32_e32 v179, 0, v25
	s_add_i32 s38, 0, 0x15000
	s_waitcnt vmcnt(0)
	s_movk_i32 s18, 0x118
	v_lshlrev_b32_e32 v32, 4, v30
	s_cmp_lg_u32 0, -1
	v_and_b32_e32 v27, 0xc0, v32
	v_or3_b32 v21, v39, v38, v21
	v_add_u32_e32 v180, 0, v21
	v_add_u32_e32 v182, 0, v20
	v_add_u32_e32 v183, 0, v24
	v_mov_b32_e32 v17, v197
	v_mov_b32_e32 v19, v197
	v_mov_b32_e32 v23, v197
	v_add_u32_e32 v184, 0, v26
	v_add3_u32 v181, s38, v31, v32
	v_cmp_gt_u32_e64 s[38:39], 32, v30
	s_mov_b32 s24, 0
	s_mov_b32 s101, 0
	v_lshl_add_u32 v176, v175, 2, v173
	v_mov_b32_e32 v187, 0
	v_mov_b32_e32 v178, 0
	v_mov_b32_e32 v226, 0
	v_mov_b32_e32 v227, 0
	v_mov_b32_e32 v228, 0
	v_mov_b32_e32 v229, 0
	v_mov_b32_e32 v230, 0
	v_mov_b32_e32 v231, 0
	v_mov_b32_e32 v232, 0
	v_mov_b32_e32 v233, 0
	v_mov_b32_e32 v234, 0
	v_mov_b32_e32 v235, 0
	v_mov_b32_e32 v236, 0
	v_mov_b32_e32 v237, 0
	v_mov_b32_e32 v238, 0
	v_mov_b32_e32 v239, 0
	v_mov_b32_e32 v240, 0
	v_mov_b32_e32 v241, 0
	s_waitcnt vmcnt(0)
; #define SBAR() __builtin_amdgcn_sched_barrier(0)
; #define SLOAD(k0) do { const char* Vt_ = (const char*)(Vh + (size_t)(k0) * ldv); const char* Kt_ = (const char*)(Kh + (size_t)(k0) * ldk); \
;     svs0 = *(const bf16x8*)(Vt_ + voff); svs1 = *(const bf16x8*)(Vt_ + vstep + voff); \
;     _Pragma("unroll") for (int i_ = 0; i_ < NKP; ++i_) sks[i_] = *(const bf16x8*)(Kt_ + koff[i_]); } while (0)
; #define SWAIT() asm volatile("s_waitcnt vmcnt(0)" ::: "memory")
; template <int DQK, int NQR>
; DEV void qkt(f32x16& p0, f32x16& p1, const char* Ks, const bf16x8* qr, const char* qlds_, int r32, int hi) {
;   constexpr int KROW = ACfg<DQK>::KROW;
;   unsigned qa = (unsigned)(uintptr_t)qlds_; asm volatile("" : "+v"(qa));
;   const __attribute__((address_space(3))) char* qlds = (const __attribute__((address_space(3))) char*)qa;
; #pragma unroll
;   for (int r = 0; r < 16; ++r) { p0[r] = 0.f; p1[r] = 0.f; }
; #pragma unroll
;   for (int d0 = 0; d0 < DQK / 16; ++d0) {
;     const int cb = (d0 * 16 + hi * 8) * 2;
;     bf16x8 b0 = *reinterpret_cast<const bf16x8*>(Ks + r32 * KROW + cb);
;     bf16x8 b1 = *reinterpret_cast<const bf16x8*>(Ks + (32 + r32) * KROW + cb);
;     bf16x8 q;
;     if (d0 < NQR) q = qr[d0 < NQR ? d0 : 0]; else q = *reinterpret_cast<const __attribute__((address_space(3))) bf16x8*>(qlds + (d0 - NQR) * 1024);
;     p0 = __builtin_amdgcn_mfma_f32_32x32x16_bf16(b0, q, p0, 0, 0, 0);
;     p1 = __builtin_amdgcn_mfma_f32_32x32x16_bf16(b1, q, p1, 0, 0, 0);
;     if (NQR < DQK / 16 && (d0 & 3) == 3) SBAR();
;   }
; }
; template <int DQK, bool WIN, bool TWO>
; DEV void attn_unit(const bf16_t* Qb, int ldq, const bf16_t* __restrict__ Kh, int ldk, const bf16_t* __restrict__ Vh, int ldv,
;                    bf16_t* Ob, int ldo, int kbeg, int NT, int q0, float sink, const float SCALE, char* lds) {
;     ...
;   for (int j = 0; j < NT; ++j) {
;     const int bf = j & 1;
;     if (j + 1 < NT) SLOAD(kbeg + (j + 1) * 64);
;     SBAR(); qkt<DQK, NQR>(pA0, pA1, K_lds + bf * KT, qr, qlds, r32, hi);
;     partialSM<WIN>(pA0, pA1, m_reg, mnA, alA, C, thr_raw, KDIFF(j));
;     RESC(alA);
;     finishSM(pA0, pA1, alA, l_reg, pa0, pa1, pa2, pa3); SBAR();
;     if (j + 1 < NT) { SWAIT(); if (bf) SWRITE(0); else SWRITE(1); }
	ds_write_b128 v179, v[0:3]
	v_and_b32_e32 v0, 32, v40
	v_and_or_b32 v0, v33, s18, v0
	s_movk_i32 s18, 0x190
	v_mad_u32_u24 v185, v175, s18, 0
	s_cselect_b32 s18, 0, 0
	v_add3_u32 v177, v27, s18, v0
	s_add_u32 s18, s41, s35
	s_addc_u32 s19, s40, 0
	s_add_u32 s18, s18, 0x2c934000
	s_addc_u32 s19, s19, 0
	s_or_b32 s2, s2, s34
	v_lshl_add_u64 v[164:165], s[18:19], 0, v[16:17]
	ds_write_b128 v180, v[4:7]
	ds_write_b128 v182, v[8:11] offset:32768
	ds_write_b128 v183, v[12:15] offset:32768
	v_mov_b32_e32 v14, v197
	v_mov_b32_e32 v15, v197
	ds_write_b128 v184, v[34:37] offset:32768
	v_lshl_add_u64 v[166:167], s[18:19], 0, v[18:19]
	v_lshl_add_u64 v[168:169], s[18:19], 0, v[22:23]
	v_lshl_add_u64 v[170:171], s[2:3], 0, v[28:29]
	v_mov_b32_e32 v0, v197
	v_mov_b32_e32 v1, v197
	v_mov_b32_e32 v2, v197
	v_mov_b32_e32 v3, v197
	v_mov_b32_e32 v4, v197
	v_mov_b32_e32 v5, v197
	v_mov_b32_e32 v6, v197
	v_mov_b32_e32 v7, v197
	v_mov_b32_e32 v8, v197
	v_mov_b32_e32 v9, v197
	v_mov_b32_e32 v10, v197
	v_mov_b32_e32 v11, v197
	v_mov_b32_e32 v12, v197
	v_mov_b32_e32 v13, v197
	v_mov_b64_e32 v[62:63], v[14:15]
	v_mov_b64_e32 v[46:47], v[14:15]
	v_mov_b64_e32 v[30:31], v[14:15]
	v_add_u32_e32 v186, v185, v196
	v_mov_b64_e32 v[60:61], v[12:13]
	v_mov_b64_e32 v[58:59], v[10:11]
	v_mov_b64_e32 v[56:57], v[8:9]
	v_mov_b64_e32 v[54:55], v[6:7]
	v_mov_b64_e32 v[52:53], v[4:5]
	v_mov_b64_e32 v[50:51], v[2:3]
	v_mov_b64_e32 v[48:49], v[0:1]
	v_mov_b64_e32 v[44:45], v[12:13]
	v_mov_b64_e32 v[42:43], v[10:11]
	v_mov_b64_e32 v[40:41], v[8:9]
	v_mov_b64_e32 v[38:39], v[6:7]
	v_mov_b64_e32 v[36:37], v[4:5]
	v_mov_b64_e32 v[34:35], v[2:3]
	v_mov_b64_e32 v[32:33], v[0:1]
	v_mov_b64_e32 v[28:29], v[12:13]
	v_mov_b64_e32 v[26:27], v[10:11]
	v_mov_b64_e32 v[24:25], v[8:9]
	v_mov_b64_e32 v[22:23], v[6:7]
	v_mov_b64_e32 v[20:21], v[4:5]
	v_mov_b64_e32 v[18:19], v[2:3]
	v_mov_b64_e32 v[16:17], v[0:1]
	s_waitcnt lgkmcnt(0)
	s_barrier
.LBB0_461:
	s_and_b32 s18, s24, 1
	s_mul_i32 s2, s18, 0x6400
	v_add_u32_e32 v202, s2, v186
	ds_read_b128 v[188:191], v202 offset:32768
	ds_read_b128 v[198:201], v202 offset:45568
	ds_read_b128 v[214:217], v202 offset:32800
	ds_read_b128 v[218:221], v202 offset:45600
	ds_read_b128 v[222:225], v202 offset:32832
	ds_read_b128 v[242:245], v202 offset:45632
	v_lshl_add_u64 v[64:65], s[64:65], 0, v[170:171]
	v_add_co_u32_e32 v66, vcc, 0x32924000, v64
	s_nop 1
	v_addc_co_u32_e32 v67, vcc, 0, v65, vcc
	v_add_co_u32_e32 v64, vcc, 0x32934000, v64
	s_nop 1
	v_addc_co_u32_e32 v65, vcc, 0, v65, vcc
	global_load_dwordx4 v[144:147], v[66:67], off
	global_load_dwordx4 v[148:151], v[64:65], off
	v_lshl_add_u64 v[64:65], s[64:65], 0, v[164:165]
	v_lshl_add_u64 v[66:67], s[64:65], 0, v[166:167]
	global_load_dwordx4 v[152:155], v[64:65], off
	global_load_dwordx4 v[156:159], v[66:67], off
	v_lshl_add_u64 v[64:65], s[64:65], 0, v[168:169]
	global_load_dwordx4 v[160:163], v[64:65], off
	s_waitcnt lgkmcnt(4)
	v_mfma_f32_32x32x16_bf16 v[80:95], v[188:191], v[140:143], v[226:241]
	v_mfma_f32_32x32x16_bf16 v[64:79], v[198:201], v[140:143], v[226:241]
	ds_read_b128 v[188:191], v202 offset:32864
	ds_read_b128 v[198:201], v202 offset:45664
	s_waitcnt lgkmcnt(4)
	v_mfma_f32_32x32x16_bf16 v[80:95], v[214:217], v[136:139], v[80:95]
	v_mfma_f32_32x32x16_bf16 v[64:79], v[218:221], v[136:139], v[64:79]
	ds_read_b128 v[214:217], v202 offset:32896
	ds_read_b128 v[218:221], v202 offset:45696
	s_waitcnt lgkmcnt(4)
	v_mfma_f32_32x32x16_bf16 v[80:95], v[222:225], v[132:135], v[80:95]
	v_mfma_f32_32x32x16_bf16 v[64:79], v[242:245], v[132:135], v[64:79]
	ds_read_b128 v[222:225], v202 offset:32928
	ds_read_b128 v[242:245], v202 offset:45728
	s_waitcnt lgkmcnt(4)
	v_mfma_f32_32x32x16_bf16 v[80:95], v[188:191], v[128:131], v[80:95]
	v_mfma_f32_32x32x16_bf16 v[64:79], v[198:201], v[128:131], v[64:79]
	ds_read_b128 v[188:191], v202 offset:32960
	ds_read_b128 v[198:201], v202 offset:45760
	s_waitcnt lgkmcnt(4)
	v_mfma_f32_32x32x16_bf16 v[80:95], v[214:217], v[124:127], v[80:95]
	v_mfma_f32_32x32x16_bf16 v[64:79], v[218:221], v[124:127], v[64:79]
	ds_read_b128 v[214:217], v202 offset:32992
	ds_read_b128 v[218:221], v202 offset:45792
	s_waitcnt lgkmcnt(4)
	v_mfma_f32_32x32x16_bf16 v[80:95], v[222:225], v[120:123], v[80:95]
	v_mfma_f32_32x32x16_bf16 v[64:79], v[242:245], v[120:123], v[64:79]
	ds_read_b128 v[222:225], v202 offset:33024
	ds_read_b128 v[242:245], v202 offset:45824
	s_waitcnt lgkmcnt(4)
	v_mfma_f32_32x32x16_bf16 v[80:95], v[188:191], v[116:119], v[80:95]
	v_mfma_f32_32x32x16_bf16 v[64:79], v[198:201], v[116:119], v[64:79]
	ds_read_b128 v[188:191], v202 offset:33056
	ds_read_b128 v[198:201], v202 offset:45856
	s_waitcnt lgkmcnt(4)
	v_mfma_f32_32x32x16_bf16 v[80:95], v[214:217], v[112:115], v[80:95]
	v_mfma_f32_32x32x16_bf16 v[64:79], v[218:221], v[112:115], v[64:79]
	ds_read_b128 v[214:217], v202 offset:33088
	ds_read_b128 v[218:221], v202 offset:45888
	s_waitcnt lgkmcnt(4)
	v_mfma_f32_32x32x16_bf16 v[80:95], v[222:225], v[108:111], v[80:95]
	v_mfma_f32_32x32x16_bf16 v[64:79], v[242:245], v[108:111], v[64:79]
	ds_read_b128 v[222:225], v202 offset:33120
	ds_read_b128 v[242:245], v202 offset:45920
	s_waitcnt lgkmcnt(4)
	v_mfma_f32_32x32x16_bf16 v[80:95], v[188:191], v[104:107], v[80:95]
	v_mfma_f32_32x32x16_bf16 v[64:79], v[198:201], v[104:107], v[64:79]
	s_waitcnt lgkmcnt(2)
	v_mfma_f32_32x32x16_bf16 v[80:95], v[214:217], v[100:103], v[80:95]
	v_mfma_f32_32x32x16_bf16 v[64:79], v[218:221], v[100:103], v[64:79]
	s_waitcnt lgkmcnt(0)
	v_mfma_f32_32x32x16_bf16 v[80:95], v[222:225], v[96:99], v[80:95]
	v_mfma_f32_32x32x16_bf16 v[64:79], v[242:245], v[96:99], v[64:79]
	s_waitcnt vmcnt(0)
	s_add_i32 s3, s101, 1
	s_cmp_eq_u32 s3, 3
	s_cselect_b32 s3, 0, s3
	s_lshl_b32 s2, s3, 14
	s_cmp_eq_u32 s3, 2
	s_cselect_b32 s3, 0x15000, s2
	s_xor_b32 s2, s18, 1
	s_mul_i32 s2, s2, 0x6400
	v_add_u32_e32 v198, s3, v179
	v_add_u32_e32 v199, s3, v180
	v_add_u32_e32 v200, s2, v182
	v_add_u32_e32 v201, s2, v183
	v_add_u32_e32 v202, s2, v184
	ds_write_b128 v198, v[144:147]
	ds_write_b128 v199, v[148:151]
	ds_write_b128 v200, v[152:155] offset:32768
	ds_write_b128 v201, v[156:159] offset:32768
	ds_write_b128 v202, v[160:163] offset:32768
	s_bitcmp0_b32 s100, 0
	s_cbranch_scc1 .Lmla_lead_mid
	s_waitcnt lgkmcnt(0)
	s_barrier
; #define SBAR() __builtin_amdgcn_sched_barrier(0)
; template <int D0, bool SPLIT = true> DEV void pv_one(f32x16& od, int vb, bf16x8 pa0, bf16x8 pa1, bf16x8 pa2, bf16x8 pa3) {
;     ...
;   } else {
;     const s16x4 l0 = tr_read<v_rd_off(D0, 0, 0)>(vb), h0 = tr_read<v_rd_off(D0, 0, 1)>(vb), l1 = tr_read<v_rd_off(D0, 1, 0)>(vb), h1 = tr_read<v_rd_off(D0, 1, 1)>(vb);
;     const s16x4 l2 = tr_read<v_rd_off(D0, 2, 0)>(vb), h2 = tr_read<v_rd_off(D0, 2, 1)>(vb), l3 = tr_read<v_rd_off(D0, 3, 0)>(vb), h3 = tr_read<v_rd_off(D0, 3, 1)>(vb);
;     asm volatile("s_waitcnt lgkmcnt(0)" ::: "memory"); SBAR();
;     od = __builtin_amdgcn_mfma_f32_32x32x16_bf16(pa0, PK(l0, h0), od, 0, 0, 0);
;     od = __builtin_amdgcn_mfma_f32_32x32x16_bf16(pa1, PK(l1, h1), od, 0, 0, 0);
; template <bool WIN>
; DEV void partialSM(f32x16& p0, f32x16& p1, float& m_reg, float& mn, float& alpha, const float C, const float thr_raw, int kdiff) {
;     ...
;   float pmax = p0[0];
; #pragma unroll
;   for (int r = 1; r < 16; ++r) pmax = fmaxf(pmax, p0[r]);
; #pragma unroll
;   for (int r = 0; r < 16; ++r) pmax = fmaxf(pmax, p1[r]);
;   { auto rr = __builtin_amdgcn_permlane32_swap(__float_as_uint(pmax), __float_as_uint(pmax), false, false);
;     pmax = fmaxf(__uint_as_float(rr[0]), __uint_as_float(rr[1])); }
;   if (__builtin_expect(__all(pmax - m_reg <= thr_raw), 1)) { mn = m_reg; alpha = 1.f; }
;   else { mn = fmaxf(m_reg, pmax); alpha = __builtin_amdgcn_exp2f((m_reg - mn) * C); m_reg = mn; }
;   const float mnC = -mn * C;
; #pragma unroll
;   for (int r = 0; r < 16; ++r) p0[r] = fmaf(p0[r], C, mnC);
; #pragma unroll
;   for (int r = 0; r < 16; ++r) p1[r] = fmaf(p1[r], C, mnC);
; #pragma unroll
;   for (int r = 0; r < 16; ++r) p0[r] = __builtin_amdgcn_exp2f(p0[r]);
; }
; DEV void finishSM(f32x16& p0, f32x16& p1, float alpha, float& l_reg, bf16x8& pa0, bf16x8& pa1, bf16x8& pa2, bf16x8& pa3) {
; #pragma unroll
;   for (int r = 0; r < 16; ++r) p1[r] = __builtin_amdgcn_exp2f(p1[r]);
;   float ps = 0;
; #pragma unroll
;   for (int r = 0; r < 16; ++r) ps += p0[r];
; #pragma unroll
;   for (int r = 0; r < 16; ++r) ps += p1[r];
;   { auto rr = __builtin_amdgcn_permlane32_swap(__float_as_uint(ps), __float_as_uint(ps), false, false);
;     ps = __uint_as_float(rr[0]) + __uint_as_float(rr[1]); }
;   l_reg = l_reg * alpha + ps;
;     ...
;   PK4(p0, 0, pa0); PK4(p0, 8, pa1); PK4(p1, 0, pa2); PK4(p1, 8, pa3);
;     ...
; }
.Lmla_lead_mid:
	v_max_f32_e32 v188, v81, v81
	v_max_f32_e32 v189, v80, v80
	v_max_f32_e32 v188, v189, v188
	v_max3_f32 v188, v188, v82, v83
	v_max3_f32 v188, v188, v84, v85
	v_max3_f32 v188, v188, v86, v87
	v_max3_f32 v188, v188, v88, v89
	v_max3_f32 v188, v188, v90, v91
	v_max3_f32 v188, v188, v92, v93
	v_max3_f32 v188, v188, v94, v95
	v_max3_f32 v188, v188, v64, v65
	v_max3_f32 v188, v188, v66, v67
	v_max3_f32 v188, v188, v68, v69
	v_max3_f32 v188, v188, v70, v71
	v_max3_f32 v188, v188, v72, v73
	v_max3_f32 v188, v188, v74, v75
	v_max3_f32 v188, v188, v76, v77
	v_max3_f32 v188, v188, v78, v79
	v_mov_b32_e32 v189, v188
	s_nop 1
	v_permlane32_swap_b32_e32 v188, v189
	v_max_f32_e32 v189, v189, v189
	v_max_f32_e32 v188, v188, v188
	v_max_f32_e32 v188, v188, v189
	v_cmp_ge_f32_e32 vcc, 0x4138aa3b, v188
	s_cmp_eq_u64 vcc, exec
	s_cbranch_scc0 .Lmla_slow
	s_cmp_eq_u32 s24, 0
	s_cbranch_scc1 .Lmla_slow
	v_mov_b32_e32 v188, 1.0
.Lmla_exp:
	v_mov_b32_e32 v189, v79
	v_exp_f32_e32 v79, v80
	v_exp_f32_e32 v190, v81
	v_exp_f32_e32 v82, v82
	v_exp_f32_e32 v83, v83
	v_exp_f32_e32 v84, v84
	v_exp_f32_e32 v191, v68
	v_add_f32_e32 v68, 0, v79
	v_exp_f32_e32 v85, v85
	v_add_f32_e32 v68, v190, v68
	v_exp_f32_e32 v86, v86
	v_add_f32_e32 v68, v82, v68
	v_exp_f32_e32 v87, v87
	v_add_f32_e32 v68, v83, v68
	v_exp_f32_e32 v88, v88
	v_add_f32_e32 v68, v84, v68
	v_exp_f32_e32 v89, v89
	v_add_f32_e32 v68, v85, v68
	v_exp_f32_e32 v90, v90
	v_add_f32_e32 v68, v86, v68
	v_exp_f32_e32 v91, v91
	v_add_f32_e32 v68, v87, v68
	v_exp_f32_e32 v92, v92
	v_add_f32_e32 v68, v88, v68
	v_exp_f32_e32 v93, v93
	v_add_f32_e32 v68, v89, v68
	v_exp_f32_e32 v94, v94
	v_add_f32_e32 v68, v90, v68
	v_exp_f32_e32 v95, v95
	v_add_f32_e32 v68, v91, v68
	v_exp_f32_e32 v64, v64
	v_add_f32_e32 v68, v92, v68
	v_exp_f32_e32 v65, v65
	v_add_f32_e32 v68, v93, v68
	v_exp_f32_e32 v66, v66
	v_add_f32_e32 v68, v94, v68
	v_exp_f32_e32 v67, v67
	v_add_f32_e32 v68, v95, v68
	v_add_f32_e32 v68, v64, v68
	v_exp_f32_e32 v198, v69
	v_add_f32_e32 v68, v65, v68
	v_exp_f32_e32 v199, v70
	v_add_f32_e32 v68, v66, v68
	v_exp_f32_e32 v200, v71
	v_add_f32_e32 v68, v67, v68
	v_exp_f32_e32 v201, v72
	v_add_f32_e32 v68, v191, v68
	v_exp_f32_e32 v202, v73
	v_add_f32_e32 v68, v198, v68
	v_exp_f32_e32 v203, v74
	v_add_f32_e32 v68, v199, v68
	v_exp_f32_e32 v213, v75
	v_add_f32_e32 v68, v200, v68
	v_exp_f32_e32 v214, v76
	v_add_f32_e32 v68, v201, v68
	v_exp_f32_e32 v215, v77
	v_add_f32_e32 v68, v202, v68
	v_exp_f32_e32 v216, v78
	v_add_f32_e32 v68, v203, v68
	v_exp_f32_e32 v189, v189
	v_add_f32_e32 v68, v213, v68
	v_add_f32_e32 v68, v214, v68
	v_add_f32_e32 v68, v215, v68
	v_add_f32_e32 v68, v216, v68
	v_add_f32_e32 v80, v189, v68
	v_mov_b32_e32 v81, v80
	v_cvt_pk_bf16_f32 v68, v79, v190
	v_cvt_pk_bf16_f32 v69, v82, v83
	v_cvt_pk_bf16_f32 v70, v84, v85
	v_cvt_pk_bf16_f32 v71, v86, v87
	v_cvt_pk_bf16_f32 v72, v88, v89
	v_cvt_pk_bf16_f32 v73, v90, v91
	v_cvt_pk_bf16_f32 v74, v92, v93
	v_cvt_pk_bf16_f32 v75, v94, v95
	v_cvt_pk_bf16_f32 v76, v64, v65
	v_cvt_pk_bf16_f32 v77, v66, v67
	v_cvt_pk_bf16_f32 v78, v191, v198
	v_cvt_pk_bf16_f32 v79, v199, v200
	v_cvt_pk_bf16_f32 v64, v201, v202
	v_cvt_pk_bf16_f32 v65, v203, v213
	v_cvt_pk_bf16_f32 v66, v214, v215
	v_cvt_pk_bf16_f32 v67, v216, v189
	v_permlane32_swap_b32_e32 v80, v81
	v_permlane32_swap_b32_e32 v68, v70
	v_permlane32_swap_b32_e32 v69, v71
	v_permlane32_swap_b32_e32 v72, v74
	v_permlane32_swap_b32_e32 v73, v75
	v_permlane32_swap_b32_e32 v76, v78
	v_permlane32_swap_b32_e32 v77, v79
	v_permlane32_swap_b32_e32 v64, v66
	v_permlane32_swap_b32_e32 v65, v67
	v_add_f32_e32 v144, v80, v81
	v_fmac_f32_e32 v144, v187, v188
	s_add_i32 s24, s24, 1
	s_lshl_b32 s2, s101, 14
	s_cmp_eq_u32 s101, 2
	s_cselect_b32 s2, 0x15000, s2
	v_add_u32_e32 v145, s2, v177
	ds_read_b64_tr_b16 v[80:81], v145 offset:0
	ds_read_b64_tr_b16 v[82:83], v145 offset:0x800
	ds_read_b64_tr_b16 v[84:85], v145 offset:0x1000
	ds_read_b64_tr_b16 v[86:87], v145 offset:0x1800
	ds_read_b64_tr_b16 v[88:89], v145 offset:0x2000
	ds_read_b64_tr_b16 v[90:91], v145 offset:0x2800
	ds_read_b64_tr_b16 v[92:93], v145 offset:0x3000
	ds_read_b64_tr_b16 v[94:95], v145 offset:0x3800
	s_waitcnt lgkmcnt(0)
	s_nop 0
	v_mfma_f32_32x32x16_bf16 v[0:15], v[68:71], v[80:83], v[0:15]
	ds_read_b64_tr_b16 v[80:81], v145 offset:0x200
	ds_read_b64_tr_b16 v[82:83], v145 offset:0xa00
	v_mfma_f32_32x32x16_bf16 v[0:15], v[72:75], v[84:87], v[0:15]
	ds_read_b64_tr_b16 v[84:85], v145 offset:0x1200
	ds_read_b64_tr_b16 v[86:87], v145 offset:0x1a00
	v_mfma_f32_32x32x16_bf16 v[0:15], v[76:79], v[88:91], v[0:15]
	ds_read_b64_tr_b16 v[88:89], v145 offset:0x2200
	ds_read_b64_tr_b16 v[90:91], v145 offset:0x2a00
	v_mfma_f32_32x32x16_bf16 v[0:15], v[64:67], v[92:95], v[0:15]
	ds_read_b64_tr_b16 v[92:93], v145 offset:0x3200
	ds_read_b64_tr_b16 v[94:95], v145 offset:0x3a00
	s_waitcnt lgkmcnt(0)
	v_mfma_f32_32x32x16_bf16 v[48:63], v[68:71], v[80:83], v[48:63]
	ds_read_b64_tr_b16 v[80:81], v145 offset:0x400
	ds_read_b64_tr_b16 v[82:83], v145 offset:0xc00
	v_mfma_f32_32x32x16_bf16 v[48:63], v[72:75], v[84:87], v[48:63]
	ds_read_b64_tr_b16 v[84:85], v145 offset:0x1400
	ds_read_b64_tr_b16 v[86:87], v145 offset:0x1c00
	v_mfma_f32_32x32x16_bf16 v[48:63], v[76:79], v[88:91], v[48:63]
	ds_read_b64_tr_b16 v[88:89], v145 offset:0x2400
	ds_read_b64_tr_b16 v[90:91], v145 offset:0x2c00
	v_mfma_f32_32x32x16_bf16 v[48:63], v[64:67], v[92:95], v[48:63]
	ds_read_b64_tr_b16 v[92:93], v145 offset:0x3400
	ds_read_b64_tr_b16 v[94:95], v145 offset:0x3c00
	s_waitcnt lgkmcnt(0)
	v_mfma_f32_32x32x16_bf16 v[32:47], v[68:71], v[80:83], v[32:47]
	ds_read_b64_tr_b16 v[80:81], v145 offset:0x600
	ds_read_b64_tr_b16 v[82:83], v145 offset:0xe00
	v_mfma_f32_32x32x16_bf16 v[32:47], v[72:75], v[84:87], v[32:47]
	ds_read_b64_tr_b16 v[84:85], v145 offset:0x1600
	ds_read_b64_tr_b16 v[86:87], v145 offset:0x1e00
	v_mfma_f32_32x32x16_bf16 v[32:47], v[76:79], v[88:91], v[32:47]
	ds_read_b64_tr_b16 v[88:89], v145 offset:0x2600
	ds_read_b64_tr_b16 v[90:91], v145 offset:0x2e00
	v_mfma_f32_32x32x16_bf16 v[32:47], v[64:67], v[92:95], v[32:47]
	ds_read_b64_tr_b16 v[92:93], v145 offset:0x3600
	ds_read_b64_tr_b16 v[94:95], v145 offset:0x3e00
	s_waitcnt lgkmcnt(0)
	v_mfma_f32_32x32x16_bf16 v[16:31], v[68:71], v[80:83], v[16:31]
	s_mov_b64 s[2:3], 0x20000
	v_lshl_add_u64 v[164:165], v[164:165], 0, s[62:63]
	v_lshl_add_u64 v[166:167], v[166:167], 0, s[62:63]
	v_lshl_add_u64 v[168:169], v[168:169], 0, s[62:63]
	v_lshl_add_u64 v[170:171], v[170:171], 0, s[2:3]
	s_add_i32 s101, s101, 1
	s_cmp_eq_u32 s101, 3
	s_cselect_b32 s101, 0, s101
	s_waitcnt lgkmcnt(0)
	v_mfma_f32_32x32x16_bf16 v[16:31], v[72:75], v[84:87], v[16:31]
	v_mfma_f32_32x32x16_bf16 v[16:31], v[76:79], v[88:91], v[16:31]
	v_mfma_f32_32x32x16_bf16 v[16:31], v[64:67], v[92:95], v[16:31]
	s_bitcmp1_b32 s100, 0
	s_cbranch_scc1 .Lmla_trail_end
	s_barrier
; template <bool WIN>
; DEV void partialSM(f32x16& p0, f32x16& p1, float& m_reg, float& mn, float& alpha, const float C, const float thr_raw, int kdiff) {
;     ...
;   if (__builtin_expect(__all(pmax - m_reg <= thr_raw), 1)) { mn = m_reg; alpha = 1.f; }
;   else { mn = fmaxf(m_reg, pmax); alpha = __builtin_amdgcn_exp2f((m_reg - mn) * C); m_reg = mn; }
.Lmla_trail_end:
	s_cmp_eq_u32 s20, s24
	s_cbranch_scc1 .LBB0_471
	v_mov_b32_e32 v187, v144
	s_branch .LBB0_461
.Lmla_slow:
	s_cmp_eq_u32 s24, 0
	s_cbranch_scc1 .Lmla_slow_first
	v_max_f32_e32 v189, 0, v188
	v_exp_f32_e64 v188, -v189
	s_branch .Lmla_slow_apply
.Lmla_slow_first:
	v_mov_b32_e32 v189, v188
	v_mov_b32_e32 v188, 1.0
.Lmla_slow_apply:
	v_add_f32_e32 v178, v178, v189
	v_sub_f32_e32 v80, v80, v189
	v_sub_f32_e32 v81, v81, v189
	v_sub_f32_e32 v82, v82, v189
	v_sub_f32_e32 v83, v83, v189
	v_sub_f32_e32 v84, v84, v189
	v_sub_f32_e32 v85, v85, v189
	v_sub_f32_e32 v86, v86, v189
	v_sub_f32_e32 v87, v87, v189
	v_sub_f32_e32 v88, v88, v189
	v_sub_f32_e32 v89, v89, v189
	v_sub_f32_e32 v90, v90, v189
	v_sub_f32_e32 v91, v91, v189
	v_sub_f32_e32 v92, v92, v189
	v_sub_f32_e32 v93, v93, v189
	v_sub_f32_e32 v94, v94, v189
	v_sub_f32_e32 v95, v95, v189
	v_sub_f32_e32 v64, v64, v189
	v_sub_f32_e32 v65, v65, v189
	v_sub_f32_e32 v66, v66, v189
	v_sub_f32_e32 v67, v67, v189
	v_sub_f32_e32 v68, v68, v189
	v_sub_f32_e32 v69, v69, v189
	v_sub_f32_e32 v70, v70, v189
	v_sub_f32_e32 v71, v71, v189
	v_sub_f32_e32 v72, v72, v189
	v_sub_f32_e32 v73, v73, v189
	v_sub_f32_e32 v74, v74, v189
	v_sub_f32_e32 v75, v75, v189
	v_sub_f32_e32 v76, v76, v189
	v_sub_f32_e32 v77, v77, v189
	v_sub_f32_e32 v78, v78, v189
	v_sub_f32_e32 v79, v79, v189
	v_sub_f32_e32 v226, v226, v189
	v_sub_f32_e32 v227, v227, v189
	v_sub_f32_e32 v228, v228, v189
	v_sub_f32_e32 v229, v229, v189
	v_sub_f32_e32 v230, v230, v189
	v_sub_f32_e32 v231, v231, v189
	v_sub_f32_e32 v232, v232, v189
	v_sub_f32_e32 v233, v233, v189
	v_sub_f32_e32 v234, v234, v189
	v_sub_f32_e32 v235, v235, v189
	v_sub_f32_e32 v236, v236, v189
	v_sub_f32_e32 v237, v237, v189
	v_sub_f32_e32 v238, v238, v189
	v_sub_f32_e32 v239, v239, v189
	v_sub_f32_e32 v240, v240, v189
	v_sub_f32_e32 v241, v241, v189
	v_cmp_gt_f32_e32 vcc, 1.0, v188
	s_cbranch_vccz .Lmla_exp
	s_and_saveexec_b64 s[2:3], s[38:39]
	ds_write_b32 v176, v188 offset:128
	s_or_b64 exec, exec, s[2:3]
	s_waitcnt lgkmcnt(0)
	v_add_u32_e32 v190, v173, v196
	ds_read_b128 v[198:201], v190 offset:224
	ds_read_b128 v[214:217], v190 offset:192
	ds_read_b128 v[218:221], v190 offset:160
	ds_read_b128 v[222:225], v190 offset:128
	s_waitcnt lgkmcnt(3)
	v_pk_mul_f32 v[12:13], v[12:13], v[198:199]
	s_waitcnt lgkmcnt(2)
	v_pk_mul_f32 v[8:9], v[8:9], v[214:215]
	s_waitcnt lgkmcnt(1)
	v_pk_mul_f32 v[4:5], v[4:5], v[218:219]
	v_pk_mul_f32 v[14:15], v[14:15], v[200:201]
	v_pk_mul_f32 v[10:11], v[10:11], v[216:217]
	v_pk_mul_f32 v[6:7], v[6:7], v[220:221]
	s_waitcnt lgkmcnt(0)
	v_pk_mul_f32 v[2:3], v[2:3], v[224:225]
	v_pk_mul_f32 v[0:1], v[0:1], v[222:223]
	v_pk_mul_f32 v[60:61], v[60:61], v[198:199]
	v_pk_mul_f32 v[56:57], v[56:57], v[214:215]
	v_pk_mul_f32 v[52:53], v[52:53], v[218:219]
	v_pk_mul_f32 v[62:63], v[62:63], v[200:201]
	v_pk_mul_f32 v[58:59], v[58:59], v[216:217]
	v_pk_mul_f32 v[54:55], v[54:55], v[220:221]
	v_pk_mul_f32 v[50:51], v[50:51], v[224:225]
	v_pk_mul_f32 v[48:49], v[48:49], v[222:223]
	v_pk_mul_f32 v[44:45], v[44:45], v[198:199]
	v_pk_mul_f32 v[40:41], v[40:41], v[214:215]
	v_pk_mul_f32 v[36:37], v[36:37], v[218:219]
	v_pk_mul_f32 v[46:47], v[46:47], v[200:201]
	v_pk_mul_f32 v[42:43], v[42:43], v[216:217]
	v_pk_mul_f32 v[38:39], v[38:39], v[220:221]
	v_pk_mul_f32 v[34:35], v[34:35], v[224:225]
	v_pk_mul_f32 v[32:33], v[32:33], v[222:223]
	v_pk_mul_f32 v[28:29], v[28:29], v[198:199]
	v_pk_mul_f32 v[24:25], v[24:25], v[214:215]
	v_pk_mul_f32 v[20:21], v[20:21], v[218:219]
	v_pk_mul_f32 v[30:31], v[30:31], v[200:201]
	v_pk_mul_f32 v[26:27], v[26:27], v[216:217]
	v_pk_mul_f32 v[22:23], v[22:23], v[220:221]
	v_pk_mul_f32 v[18:19], v[18:19], v[224:225]
	v_pk_mul_f32 v[16:17], v[16:17], v[222:223]
	s_branch .Lmla_exp
.LBB0_471:
	s_and_b32 s18, s20, 1
	s_mul_i32 s2, s18, 0x6400
	v_add3_u32 v145, v185, s2, v196
	ds_read_b128 v[64:67], v145 offset:32768
	s_waitcnt lgkmcnt(0)
	v_mfma_f32_32x32x16_bf16 v[80:95], v[64:67], v[140:143], 0
	ds_read_b128 v[64:67], v145 offset:45568
	s_waitcnt lgkmcnt(0)
	v_mfma_f32_32x32x16_bf16 v[64:79], v[64:67], v[140:143], 0
	ds_read_b128 v[140:143], v145 offset:32800
	s_waitcnt lgkmcnt(0)
	v_mfma_f32_32x32x16_bf16 v[80:95], v[140:143], v[136:139], v[80:95]
	ds_read_b128 v[140:143], v145 offset:45600
	s_waitcnt lgkmcnt(0)
	v_mfma_f32_32x32x16_bf16 v[64:79], v[140:143], v[136:139], v[64:79]
	ds_read_b128 v[136:139], v145 offset:32832
	s_waitcnt lgkmcnt(0)
	v_mfma_f32_32x32x16_bf16 v[80:95], v[136:139], v[132:135], v[80:95]
	ds_read_b128 v[136:139], v145 offset:45632
	s_waitcnt lgkmcnt(0)
	v_mfma_f32_32x32x16_bf16 v[64:79], v[136:139], v[132:135], v[64:79]
	ds_read_b128 v[132:135], v145 offset:32864
	s_waitcnt lgkmcnt(0)
	v_mfma_f32_32x32x16_bf16 v[80:95], v[132:135], v[128:131], v[80:95]
	ds_read_b128 v[132:135], v145 offset:45664
	s_waitcnt lgkmcnt(0)
	v_mfma_f32_32x32x16_bf16 v[64:79], v[132:135], v[128:131], v[64:79]
	ds_read_b128 v[128:131], v145 offset:32896
	s_waitcnt lgkmcnt(0)
	v_mfma_f32_32x32x16_bf16 v[80:95], v[128:131], v[124:127], v[80:95]
	ds_read_b128 v[128:131], v145 offset:45696
	s_waitcnt lgkmcnt(0)
	v_mfma_f32_32x32x16_bf16 v[64:79], v[128:131], v[124:127], v[64:79]
	ds_read_b128 v[124:127], v145 offset:32928
	s_waitcnt lgkmcnt(0)
	v_mfma_f32_32x32x16_bf16 v[80:95], v[124:127], v[120:123], v[80:95]
	ds_read_b128 v[124:127], v145 offset:45728
	s_waitcnt lgkmcnt(0)
	v_mfma_f32_32x32x16_bf16 v[64:79], v[124:127], v[120:123], v[64:79]
	ds_read_b128 v[120:123], v145 offset:32960
	s_waitcnt lgkmcnt(0)
	v_mfma_f32_32x32x16_bf16 v[80:95], v[120:123], v[116:119], v[80:95]
	ds_read_b128 v[120:123], v145 offset:45760
	s_waitcnt lgkmcnt(0)
; #define SBAR() __builtin_amdgcn_sched_barrier(0)
; template <bool WIN>
; DEV void partialSM(f32x16& p0, f32x16& p1, float& m_reg, float& mn, float& alpha, const float C, const float thr_raw, int kdiff) {
;     ...
;   float pmax = p0[0];
; #pragma unroll
;   for (int r = 1; r < 16; ++r) pmax = fmaxf(pmax, p0[r]);
; #pragma unroll
;   for (int r = 0; r < 16; ++r) pmax = fmaxf(pmax, p1[r]);
;   { auto rr = __builtin_amdgcn_permlane32_swap(__float_as_uint(pmax), __float_as_uint(pmax), false, false);
;     pmax = fmaxf(__uint_as_float(rr[0]), __uint_as_float(rr[1])); }
;   if (__builtin_expect(__all(pmax - m_reg <= thr_raw), 1)) { mn = m_reg; alpha = 1.f; }
;   else { mn = fmaxf(m_reg, pmax); alpha = __builtin_amdgcn_exp2f((m_reg - mn) * C); m_reg = mn; }
; template <int DQK, int NQR>
; DEV void qkt(f32x16& p0, f32x16& p1, const char* Ks, const bf16x8* qr, const char* qlds_, int r32, int hi) {
;   constexpr int KROW = ACfg<DQK>::KROW;
;   unsigned qa = (unsigned)(uintptr_t)qlds_; asm volatile("" : "+v"(qa));
;   const __attribute__((address_space(3))) char* qlds = (const __attribute__((address_space(3))) char*)qa;
; #pragma unroll
;   for (int r = 0; r < 16; ++r) { p0[r] = 0.f; p1[r] = 0.f; }
; #pragma unroll
;   for (int d0 = 0; d0 < DQK / 16; ++d0) {
;     const int cb = (d0 * 16 + hi * 8) * 2;
;     bf16x8 b0 = *reinterpret_cast<const bf16x8*>(Ks + r32 * KROW + cb);
;     bf16x8 b1 = *reinterpret_cast<const bf16x8*>(Ks + (32 + r32) * KROW + cb);
;     bf16x8 q;
;     if (d0 < NQR) q = qr[d0 < NQR ? d0 : 0]; else q = *reinterpret_cast<const __attribute__((address_space(3))) bf16x8*>(qlds + (d0 - NQR) * 1024);
;     p0 = __builtin_amdgcn_mfma_f32_32x32x16_bf16(b0, q, p0, 0, 0, 0);
;     p1 = __builtin_amdgcn_mfma_f32_32x32x16_bf16(b1, q, p1, 0, 0, 0);
;     if (NQR < DQK / 16 && (d0 & 3) == 3) SBAR();
;   }
; }
	v_mfma_f32_32x32x16_bf16 v[64:79], v[120:123], v[116:119], v[64:79]
	ds_read_b128 v[116:119], v145 offset:32992
	s_waitcnt lgkmcnt(0)
	v_mfma_f32_32x32x16_bf16 v[80:95], v[116:119], v[112:115], v[80:95]
	ds_read_b128 v[116:119], v145 offset:45792
	s_waitcnt lgkmcnt(0)
	v_mfma_f32_32x32x16_bf16 v[64:79], v[116:119], v[112:115], v[64:79]
	ds_read_b128 v[112:115], v145 offset:33024
	s_waitcnt lgkmcnt(0)
	v_mfma_f32_32x32x16_bf16 v[80:95], v[112:115], v[108:111], v[80:95]
	ds_read_b128 v[112:115], v145 offset:45824
	s_waitcnt lgkmcnt(0)
	v_mfma_f32_32x32x16_bf16 v[64:79], v[112:115], v[108:111], v[64:79]
	ds_read_b128 v[108:111], v145 offset:33056
	s_waitcnt lgkmcnt(0)
	v_mfma_f32_32x32x16_bf16 v[80:95], v[108:111], v[104:107], v[80:95]
	ds_read_b128 v[108:111], v145 offset:45856
	s_waitcnt lgkmcnt(0)
	v_mfma_f32_32x32x16_bf16 v[64:79], v[108:111], v[104:107], v[64:79]
	ds_read_b128 v[104:107], v145 offset:33088
	s_waitcnt lgkmcnt(0)
	v_mfma_f32_32x32x16_bf16 v[80:95], v[104:107], v[100:103], v[80:95]
	ds_read_b128 v[104:107], v145 offset:33120
	s_waitcnt lgkmcnt(0)
	v_mfma_f32_32x32x16_bf16 v[80:95], v[104:107], v[96:99], v[80:95]
	ds_read_b128 v[104:107], v145 offset:45888
	ds_read_b128 v[108:111], v145 offset:45920
	s_waitcnt lgkmcnt(1)
	v_mfma_f32_32x32x16_bf16 v[64:79], v[104:107], v[100:103], v[64:79]
	s_nop 7
	v_max_f32_e32 v112, v81, v81
	v_max_f32_e32 v113, v80, v80
	v_max_f32_e32 v112, v113, v112
	v_max3_f32 v100, v112, v82, v83
	v_max3_f32 v100, v100, v84, v85
	v_max3_f32 v100, v100, v86, v87
	v_max3_f32 v100, v100, v88, v89
	s_waitcnt lgkmcnt(0)
	v_mfma_f32_32x32x16_bf16 v[64:79], v[108:111], v[96:99], v[64:79]
	v_max3_f32 v100, v100, v90, v91
	v_max3_f32 v100, v100, v92, v93
	v_max3_f32 v100, v100, v94, v95
	s_nop 8
	v_max3_f32 v96, v100, v64, v65
	v_max3_f32 v96, v96, v66, v67
	v_max3_f32 v96, v96, v68, v69
	v_max3_f32 v96, v96, v70, v71
	v_max3_f32 v96, v96, v72, v73
	v_max3_f32 v96, v96, v74, v75
	v_max3_f32 v96, v96, v76, v77
	v_max3_f32 v96, v96, v78, v79
	v_mov_b32_e32 v97, v96
	s_nop 1
	v_permlane32_swap_b32_e32 v96, v97
	v_max_f32_e32 v97, v97, v97
	v_max_f32_e32 v96, v96, v96
	v_max_f32_e32 v96, v96, v97
	v_max_f32_e32 v97, v178, v178
	v_max_f32_e32 v97, v97, v96
	v_sub_f32_e32 v98, v96, v178
	v_sub_f32_e32 v96, v178, v97
	v_mul_f32_e32 v96, 1.0, v96
	v_exp_f32_e32 v96, v96
	v_cmp_ge_f32_e32 vcc, 0x4138aa3b, v98
	s_cmp_eq_u64 vcc, exec
	s_cselect_b64 s[40:41], -1, 0
	v_cndmask_b32_e64 v96, v96, 1.0, s[40:41]
	v_cmp_gt_f32_e32 vcc, 1.0, v96
	s_cbranch_vccz .LBB0_475
	s_and_saveexec_b64 s[2:3], s[38:39]
	ds_write_b32 v176, v96 offset:128
	s_or_b64 exec, exec, s[2:3]
	s_waitcnt lgkmcnt(0)
	v_add_u32_e32 v110, v173, v196
	ds_read_b128 v[98:101], v110 offset:224
	ds_read_b128 v[102:105], v110 offset:192
	ds_read_b128 v[106:109], v110 offset:160
	ds_read_b128 v[110:113], v110 offset:128
	s_waitcnt lgkmcnt(3)
	v_pk_mul_f32 v[12:13], v[12:13], v[98:99]
	s_waitcnt lgkmcnt(2)
	v_pk_mul_f32 v[8:9], v[8:9], v[102:103]
	s_waitcnt lgkmcnt(1)
	v_pk_mul_f32 v[4:5], v[4:5], v[106:107]
	v_pk_mul_f32 v[14:15], v[14:15], v[100:101]
	v_pk_mul_f32 v[10:11], v[10:11], v[104:105]
	v_pk_mul_f32 v[6:7], v[6:7], v[108:109]
	s_waitcnt lgkmcnt(0)
	v_pk_mul_f32 v[2:3], v[2:3], v[112:113]
	v_pk_mul_f32 v[0:1], v[0:1], v[110:111]
	v_pk_mul_f32 v[60:61], v[60:61], v[98:99]
	v_pk_mul_f32 v[56:57], v[56:57], v[102:103]
	v_pk_mul_f32 v[52:53], v[52:53], v[106:107]
	v_pk_mul_f32 v[62:63], v[62:63], v[100:101]
	v_pk_mul_f32 v[58:59], v[58:59], v[104:105]
	v_pk_mul_f32 v[54:55], v[54:55], v[108:109]
	v_pk_mul_f32 v[50:51], v[50:51], v[112:113]
	v_pk_mul_f32 v[48:49], v[48:49], v[110:111]
	v_pk_mul_f32 v[44:45], v[44:45], v[98:99]
	v_pk_mul_f32 v[40:41], v[40:41], v[102:103]
	v_pk_mul_f32 v[36:37], v[36:37], v[106:107]
	v_pk_mul_f32 v[46:47], v[46:47], v[100:101]
	v_pk_mul_f32 v[42:43], v[42:43], v[104:105]
	v_pk_mul_f32 v[38:39], v[38:39], v[108:109]
	v_pk_mul_f32 v[34:35], v[34:35], v[112:113]
	v_pk_mul_f32 v[32:33], v[32:33], v[110:111]
	v_pk_mul_f32 v[28:29], v[28:29], v[98:99]
	v_pk_mul_f32 v[24:25], v[24:25], v[102:103]
	v_pk_mul_f32 v[20:21], v[20:21], v[106:107]
	v_pk_mul_f32 v[30:31], v[30:31], v[100:101]
	v_pk_mul_f32 v[26:27], v[26:27], v[104:105]
	v_pk_mul_f32 v[22:23], v[22:23], v[108:109]
	v_pk_mul_f32 v[18:19], v[18:19], v[112:113]
	v_pk_mul_f32 v[16:17], v[16:17], v[110:111]
; template <bool WIN>
; DEV void partialSM(f32x16& p0, f32x16& p1, float& m_reg, float& mn, float& alpha, const float C, const float thr_raw, int kdiff) {
;     ...
;   const float mnC = -mn * C;
; #pragma unroll
;   for (int r = 0; r < 16; ++r) p0[r] = fmaf(p0[r], C, mnC);
; #pragma unroll
;   for (int r = 0; r < 16; ++r) p1[r] = fmaf(p1[r], C, mnC);
; #pragma unroll
;   for (int r = 0; r < 16; ++r) p0[r] = __builtin_amdgcn_exp2f(p0[r]);
; }
; DEV void finishSM(f32x16& p0, f32x16& p1, float alpha, float& l_reg, bf16x8& pa0, bf16x8& pa1, bf16x8& pa2, bf16x8& pa3) {
; #pragma unroll
;   for (int r = 0; r < 16; ++r) p1[r] = __builtin_amdgcn_exp2f(p1[r]);
;   float ps = 0;
; #pragma unroll
;   for (int r = 0; r < 16; ++r) ps += p0[r];
; #pragma unroll
;   for (int r = 0; r < 16; ++r) ps += p1[r];
;   { auto rr = __builtin_amdgcn_permlane32_swap(__float_as_uint(ps), __float_as_uint(ps), false, false);
;     ps = __uint_as_float(rr[0]) + __uint_as_float(rr[1]); }
;   l_reg = l_reg * alpha + ps;
;     ...
;   PK4(p0, 0, pa0); PK4(p0, 8, pa1); PK4(p1, 0, pa2); PK4(p1, 8, pa3);
;     ...
; }
; template <int DQK, bool WIN, bool TWO>
; DEV void attn_unit(const bf16_t* Qb, int ldq, const bf16_t* __restrict__ Kh, int ldk, const bf16_t* __restrict__ Vh, int ldv,
;                    bf16_t* Ob, int ldo, int kbeg, int NT, int q0, float sink, const float SCALE, char* lds) {
;     ...
;     pv_d0<false>(o, vb0 + bf * SHM_V, pa0, pa1, pa2, pa3);
;     ...
;   if (WIN) l_reg += __builtin_amdgcn_exp2f(sink * 1.4426950408889634f - m_reg * C);
;   if (hi == 0) li_l[r32] = l_reg; asm volatile("s_waitcnt lgkmcnt(0)" ::: "memory");
.LBB0_475:
	v_cndmask_b32_e64 v97, v97, v178, s[40:41]
	v_mul_f32_e32 v97, -1.0, v97
	v_fmamk_f32 v80, v80, 0x3f800000, v97
	v_fmamk_f32 v81, v81, 0x3f800000, v97
	v_fmamk_f32 v82, v82, 0x3f800000, v97
	v_fmamk_f32 v83, v83, 0x3f800000, v97
	v_fmamk_f32 v84, v84, 0x3f800000, v97
	v_fmamk_f32 v85, v85, 0x3f800000, v97
	v_fmamk_f32 v86, v86, 0x3f800000, v97
	v_fmamk_f32 v87, v87, 0x3f800000, v97
	v_fmamk_f32 v88, v88, 0x3f800000, v97
	v_fmamk_f32 v89, v89, 0x3f800000, v97
	v_fmamk_f32 v90, v90, 0x3f800000, v97
	v_fmamk_f32 v91, v91, 0x3f800000, v97
	v_fmamk_f32 v92, v92, 0x3f800000, v97
	v_fmamk_f32 v93, v93, 0x3f800000, v97
	v_fmamk_f32 v94, v94, 0x3f800000, v97
	v_fmamk_f32 v95, v95, 0x3f800000, v97
	v_fmamk_f32 v64, v64, 0x3f800000, v97
	v_fmamk_f32 v65, v65, 0x3f800000, v97
	v_fmamk_f32 v66, v66, 0x3f800000, v97
	v_fmamk_f32 v67, v67, 0x3f800000, v97
	v_fmamk_f32 v68, v68, 0x3f800000, v97
	v_fmamk_f32 v69, v69, 0x3f800000, v97
	v_fmamk_f32 v70, v70, 0x3f800000, v97
	v_fmamk_f32 v71, v71, 0x3f800000, v97
	v_fmamk_f32 v72, v72, 0x3f800000, v97
	v_fmamk_f32 v73, v73, 0x3f800000, v97
	v_fmamk_f32 v74, v74, 0x3f800000, v97
	v_fmamk_f32 v75, v75, 0x3f800000, v97
	v_fmamk_f32 v76, v76, 0x3f800000, v97
	v_fmamk_f32 v77, v77, 0x3f800000, v97
	v_fmamk_f32 v78, v78, 0x3f800000, v97
	v_fmac_f32_e32 v97, 1.0, v79
	v_exp_f32_e32 v79, v80
	v_exp_f32_e32 v80, v81
	v_exp_f32_e32 v81, v82
	v_exp_f32_e32 v82, v83
	v_exp_f32_e32 v83, v84
	v_exp_f32_e32 v84, v85
	v_exp_f32_e32 v85, v86
	v_exp_f32_e32 v86, v87
	v_exp_f32_e32 v87, v88
	v_exp_f32_e32 v88, v89
	v_exp_f32_e32 v89, v90
	v_exp_f32_e32 v90, v91
	v_exp_f32_e32 v91, v92
	v_exp_f32_e32 v92, v93
	v_exp_f32_e32 v93, v94
	v_exp_f32_e32 v94, v95
	v_exp_f32_e32 v95, v64
	v_add_f32_e32 v64, 0, v79
	v_add_f32_e32 v64, v80, v64
	v_add_f32_e32 v64, v81, v64
	v_add_f32_e32 v64, v82, v64
	v_add_f32_e32 v64, v83, v64
	v_add_f32_e32 v64, v84, v64
	v_add_f32_e32 v64, v85, v64
	v_add_f32_e32 v64, v86, v64
	v_add_f32_e32 v64, v87, v64
	v_add_f32_e32 v64, v88, v64
	v_add_f32_e32 v64, v89, v64
	v_add_f32_e32 v64, v90, v64
	v_add_f32_e32 v64, v91, v64
	v_exp_f32_e32 v98, v65
	v_add_f32_e32 v64, v92, v64
	v_exp_f32_e32 v99, v66
	v_add_f32_e32 v64, v93, v64
	v_exp_f32_e32 v100, v67
	v_add_f32_e32 v64, v94, v64
	v_exp_f32_e32 v101, v68
	v_add_f32_e32 v64, v95, v64
	v_exp_f32_e32 v102, v69
	v_add_f32_e32 v64, v98, v64
	v_exp_f32_e32 v103, v70
	v_add_f32_e32 v64, v99, v64
	v_exp_f32_e32 v104, v71
	v_add_f32_e32 v64, v100, v64
	v_exp_f32_e32 v105, v72
	v_add_f32_e32 v64, v101, v64
	v_exp_f32_e32 v106, v73
	v_add_f32_e32 v64, v102, v64
	v_exp_f32_e32 v107, v74
	v_add_f32_e32 v64, v103, v64
	v_exp_f32_e32 v108, v75
	v_add_f32_e32 v64, v104, v64
	v_exp_f32_e32 v109, v76
	v_add_f32_e32 v64, v105, v64
	v_exp_f32_e32 v110, v77
	v_add_f32_e32 v64, v106, v64
	v_exp_f32_e32 v111, v78
	v_add_f32_e32 v64, v107, v64
	v_exp_f32_e32 v97, v97
	v_add_f32_e32 v64, v108, v64
	v_add_f32_e32 v64, v109, v64
	v_add_f32_e32 v64, v110, v64
	v_add_f32_e32 v64, v111, v64
	v_add_f32_e32 v64, v97, v64
	v_mov_b32_e32 v65, v64
	s_nop 1
	v_permlane32_swap_b32_e32 v64, v65
	v_cvt_pk_bf16_f32 v66, v79, v80
	v_cvt_pk_bf16_f32 v67, v81, v82
	v_cvt_pk_bf16_f32 v68, v83, v84
	v_cvt_pk_bf16_f32 v69, v85, v86
	v_cvt_pk_bf16_f32 v70, v87, v88
	v_cvt_pk_bf16_f32 v71, v89, v90
	v_cvt_pk_bf16_f32 v72, v91, v92
	v_cvt_pk_bf16_f32 v73, v93, v94
	v_cvt_pk_bf16_f32 v74, v95, v98
	v_cvt_pk_bf16_f32 v75, v99, v100
	v_cvt_pk_bf16_f32 v76, v101, v102
	v_cvt_pk_bf16_f32 v77, v103, v104
	v_cvt_pk_bf16_f32 v78, v105, v106
	v_cvt_pk_bf16_f32 v79, v107, v108
	v_cvt_pk_bf16_f32 v80, v109, v110
	v_cvt_pk_bf16_f32 v81, v111, v97
	v_permlane32_swap_b32_e32 v66, v68
	v_permlane32_swap_b32_e32 v67, v69
	v_permlane32_swap_b32_e32 v70, v72
	v_permlane32_swap_b32_e32 v71, v73
	v_permlane32_swap_b32_e32 v74, v76
	v_permlane32_swap_b32_e32 v75, v77
	v_permlane32_swap_b32_e32 v78, v80
	v_permlane32_swap_b32_e32 v79, v81
	s_lshl_b32 s2, s101, 14
	s_cmp_eq_u32 s101, 2
	s_cselect_b32 s2, 0x15000, s2
	v_add_u32_e32 v94, s2, v177
	ds_read_b64_tr_b16 v[82:83], v94 offset:0
	ds_read_b64_tr_b16 v[84:85], v94 offset:0x800
	ds_read_b64_tr_b16 v[86:87], v94 offset:0x1000
	ds_read_b64_tr_b16 v[88:89], v94 offset:0x1800
	ds_read_b64_tr_b16 v[90:91], v94 offset:0x2000
	ds_read_b64_tr_b16 v[92:93], v94 offset:0x2800
	ds_read_b64_tr_b16 v[98:99], v94 offset:0x3000
	ds_read_b64_tr_b16 v[100:101], v94 offset:0x3800
	s_waitcnt lgkmcnt(0)
	s_nop 0
	v_mfma_f32_32x32x16_bf16 v[0:15], v[66:69], v[82:85], v[0:15]
	ds_read_b64_tr_b16 v[82:83], v94 offset:0x200
	ds_read_b64_tr_b16 v[84:85], v94 offset:0xa00
	v_mfma_f32_32x32x16_bf16 v[0:15], v[70:73], v[86:89], v[0:15]
	ds_read_b64_tr_b16 v[86:87], v94 offset:0x1200
	ds_read_b64_tr_b16 v[88:89], v94 offset:0x1a00
	v_mfma_f32_32x32x16_bf16 v[0:15], v[74:77], v[90:93], v[0:15]
	ds_read_b64_tr_b16 v[90:91], v94 offset:0x2200
	ds_read_b64_tr_b16 v[92:93], v94 offset:0x2a00
	v_mfma_f32_32x32x16_bf16 v[0:15], v[78:81], v[98:101], v[0:15]
	ds_read_b64_tr_b16 v[98:99], v94 offset:0x3200
	ds_read_b64_tr_b16 v[100:101], v94 offset:0x3a00
	s_waitcnt lgkmcnt(0)
	v_mfma_f32_32x32x16_bf16 v[48:63], v[66:69], v[82:85], v[48:63]
	ds_read_b64_tr_b16 v[82:83], v94 offset:0x400
	ds_read_b64_tr_b16 v[84:85], v94 offset:0xc00
	v_mfma_f32_32x32x16_bf16 v[48:63], v[70:73], v[86:89], v[48:63]
	ds_read_b64_tr_b16 v[86:87], v94 offset:0x1400
	ds_read_b64_tr_b16 v[88:89], v94 offset:0x1c00
	v_mfma_f32_32x32x16_bf16 v[48:63], v[74:77], v[90:93], v[48:63]
	ds_read_b64_tr_b16 v[90:91], v94 offset:0x2400
	ds_read_b64_tr_b16 v[92:93], v94 offset:0x2c00
	v_mfma_f32_32x32x16_bf16 v[48:63], v[78:81], v[98:101], v[48:63]
	ds_read_b64_tr_b16 v[98:99], v94 offset:0x3400
	ds_read_b64_tr_b16 v[100:101], v94 offset:0x3c00
	s_waitcnt lgkmcnt(0)
	v_mfma_f32_32x32x16_bf16 v[32:47], v[66:69], v[82:85], v[32:47]
	ds_read_b64_tr_b16 v[82:83], v94 offset:0x600
	ds_read_b64_tr_b16 v[84:85], v94 offset:0xe00
	v_mfma_f32_32x32x16_bf16 v[32:47], v[70:73], v[86:89], v[32:47]
	ds_read_b64_tr_b16 v[86:87], v94 offset:0x1600
	ds_read_b64_tr_b16 v[88:89], v94 offset:0x1e00
	v_mfma_f32_32x32x16_bf16 v[32:47], v[74:77], v[90:93], v[32:47]
	ds_read_b64_tr_b16 v[90:91], v94 offset:0x2600
	ds_read_b64_tr_b16 v[92:93], v94 offset:0x2e00
	v_mfma_f32_32x32x16_bf16 v[32:47], v[78:81], v[98:101], v[32:47]
	ds_read_b64_tr_b16 v[98:99], v94 offset:0x3600
	ds_read_b64_tr_b16 v[100:101], v94 offset:0x3e00
	s_waitcnt lgkmcnt(0)
	v_mfma_f32_32x32x16_bf16 v[16:31], v[66:69], v[82:85], v[16:31]
	s_barrier
	v_mfma_f32_32x32x16_bf16 v[16:31], v[70:73], v[86:89], v[16:31]
	v_mfma_f32_32x32x16_bf16 v[16:31], v[74:77], v[90:93], v[16:31]
	v_mfma_f32_32x32x16_bf16 v[16:31], v[78:81], v[98:101], v[16:31]
	s_and_saveexec_b64 s[2:3], s[38:39]
	s_cbranch_execz .LBB0_459
	v_add_f32_e32 v64, v64, v65
	v_fmac_f32_e32 v64, v144, v96
	ds_write_b32 v176, v64
	s_branch .LBB0_459

; DEV float bf2f(bf16_t u) { return __uint_as_float(((unsigned)u) << 16); }
; #define SBAR() __builtin_amdgcn_sched_barrier(0)
; template <int MI, bool ROWSS>
; DEV void gemm_mainloop(f32x16 (&acc)[MI][4], float (&ss)[MI], const bf16_t* __restrict__ A, int lda, const bf16_t* __restrict__ Bt, int ldb, int K, char* lds) {
;     ...
;   for (int kt = 0; kt < nk; ++kt) {
;     const char* base = lds + (kt & 1) * C::STAGE;
;     SBAR();
; #pragma unroll
;     for (int ks = 0; ks < 4; ++ks) {
;       bf16x8 a[MI], b[4];
; #pragma unroll
;       for (int mi = 0; mi < MI; ++mi) a[mi] = *(const bf16x8*)(base + aoff + mi * 32 * G_ROWB + ks * 32);
; #pragma unroll
;       for (int nf = 0; nf < 4; ++nf) b[nf] = *(const bf16x8*)(base + boff + nf * 32 * G_ROWB + ks * 32);
;       if (ROWSS) {
; #pragma unroll
;         for (int mi = 0; mi < MI; ++mi)
; #pragma unroll
;           for (int j = 0; j < 8; ++j) { float f = bf2f((bf16_t)a[mi][j]); ss[mi] += f * f; }
;       }
;       __builtin_amdgcn_s_setprio(1);
; #pragma unroll
;       for (int mi = 0; mi < MI; ++mi)
; #pragma unroll
;         for (int nf = 0; nf < 4; ++nf) acc[mi][nf] = __builtin_amdgcn_mfma_f32_32x32x16_bf16(a[mi], b[nf], acc[mi][nf], 0, 0, 0);
;       __builtin_amdgcn_s_setprio(0);
;     }
.LBB0_1007:
	s_add_i32 s0, 0, 0x12000
	s_waitcnt vmcnt(3)
	v_add3_u32 v145, s0, v213, v214
	v_add3_u32 v162, s0, v215, v214
	ds_read_b128 v[132:135], v145
	ds_read_b128 v[128:131], v145 offset:4608
	ds_read_b128 v[136:139], v162 offset:36864
	ds_read_b128 v[140:143], v162 offset:41472
	s_waitcnt vmcnt(2)
	ds_read_b128 v[146:149], v162 offset:46080
	s_waitcnt vmcnt(1)
	ds_read_b128 v[150:153], v162 offset:50688
	s_waitcnt lgkmcnt(5)
	v_lshlrev_b32_e32 v144, 16, v132
	v_fma_f32 v144, v144, v144, v198
	v_and_b32_e32 v154, 0xffff0000, v132
	v_fmac_f32_e32 v144, v154, v154
	v_lshlrev_b32_e32 v154, 16, v133
	v_fmac_f32_e32 v144, v154, v154
	v_and_b32_e32 v154, 0xffff0000, v133
	v_fmac_f32_e32 v144, v154, v154
	v_lshlrev_b32_e32 v154, 16, v134
	v_fmac_f32_e32 v144, v154, v154
	v_and_b32_e32 v154, 0xffff0000, v134
	v_fmac_f32_e32 v144, v154, v154
	v_lshlrev_b32_e32 v154, 16, v135
	v_fmac_f32_e32 v144, v154, v154
	v_and_b32_e32 v154, 0xffff0000, v135
	v_fmac_f32_e32 v144, v154, v154
	s_setprio 1
	s_waitcnt lgkmcnt(3)
	v_mfma_f32_32x32x16_bf16 v[112:127], v[132:135], v[136:139], v[112:127]
	s_waitcnt lgkmcnt(2)
	v_mfma_f32_32x32x16_bf16 v[96:111], v[132:135], v[140:143], v[96:111]
	s_waitcnt lgkmcnt(1)
	v_mfma_f32_32x32x16_bf16 v[80:95], v[132:135], v[146:149], v[80:95]
	s_waitcnt lgkmcnt(0)
	v_mfma_f32_32x32x16_bf16 v[64:79], v[132:135], v[150:153], v[64:79]
	v_mfma_f32_32x32x16_bf16 v[48:63], v[128:131], v[136:139], v[48:63]
	v_mfma_f32_32x32x16_bf16 v[32:47], v[128:131], v[140:143], v[32:47]
	v_mfma_f32_32x32x16_bf16 v[16:31], v[128:131], v[146:149], v[16:31]
	v_mfma_f32_32x32x16_bf16 v[0:15], v[128:131], v[150:153], v[0:15]
	s_setprio 0
	ds_read_b128 v[136:139], v145 offset:32
	ds_read_b128 v[132:135], v145 offset:4640
	ds_read_b128 v[140:143], v162 offset:36896
	ds_read_b128 v[146:149], v162 offset:41504
	ds_read_b128 v[150:153], v162 offset:46112
	s_waitcnt vmcnt(0)
	ds_read_b128 v[154:157], v162 offset:50720
	s_waitcnt lgkmcnt(5)
	v_lshlrev_b32_e32 v158, 16, v136
	v_fmac_f32_e32 v144, v158, v158
	v_and_b32_e32 v158, 0xffff0000, v136
	v_fmac_f32_e32 v144, v158, v158
	v_lshlrev_b32_e32 v158, 16, v137
	v_fmac_f32_e32 v144, v158, v158
	v_and_b32_e32 v158, 0xffff0000, v137
	v_fmac_f32_e32 v144, v158, v158
	v_lshlrev_b32_e32 v158, 16, v138
	v_fmac_f32_e32 v144, v158, v158
	v_and_b32_e32 v158, 0xffff0000, v138
	v_fmac_f32_e32 v144, v158, v158
	v_lshlrev_b32_e32 v158, 16, v139
	v_fmac_f32_e32 v144, v158, v158
	v_and_b32_e32 v158, 0xffff0000, v139
	v_fmac_f32_e32 v144, v158, v158
	s_setprio 1
	s_waitcnt lgkmcnt(3)
	v_mfma_f32_32x32x16_bf16 v[112:127], v[136:139], v[140:143], v[112:127]
	s_waitcnt lgkmcnt(2)
	v_mfma_f32_32x32x16_bf16 v[96:111], v[136:139], v[146:149], v[96:111]
	s_waitcnt lgkmcnt(1)
	v_mfma_f32_32x32x16_bf16 v[80:95], v[136:139], v[150:153], v[80:95]
	s_waitcnt lgkmcnt(0)
	v_mfma_f32_32x32x16_bf16 v[64:79], v[136:139], v[154:157], v[64:79]
	v_mfma_f32_32x32x16_bf16 v[48:63], v[132:135], v[140:143], v[48:63]
	v_mfma_f32_32x32x16_bf16 v[32:47], v[132:135], v[146:149], v[32:47]
	v_mfma_f32_32x32x16_bf16 v[16:31], v[132:135], v[150:153], v[16:31]
	v_mfma_f32_32x32x16_bf16 v[0:15], v[132:135], v[154:157], v[0:15]
	s_setprio 0
	ds_read_b128 v[140:143], v145 offset:64
	ds_read_b128 v[136:139], v145 offset:4672
	ds_read_b128 v[146:149], v162 offset:36928
	ds_read_b128 v[150:153], v162 offset:41536
	ds_read_b128 v[154:157], v162 offset:46144
	ds_read_b128 v[158:161], v162 offset:50752
	s_waitcnt lgkmcnt(5)
	v_lshlrev_b32_e32 v163, 16, v140
	v_fmac_f32_e32 v144, v163, v163
	v_and_b32_e32 v163, 0xffff0000, v140
	v_fmac_f32_e32 v144, v163, v163
	v_lshlrev_b32_e32 v163, 16, v141
	v_fmac_f32_e32 v144, v163, v163
	v_and_b32_e32 v163, 0xffff0000, v141
	v_fmac_f32_e32 v144, v163, v163
	v_lshlrev_b32_e32 v163, 16, v142
	v_fmac_f32_e32 v144, v163, v163
	v_and_b32_e32 v163, 0xffff0000, v142
	v_fmac_f32_e32 v144, v163, v163
	v_lshlrev_b32_e32 v163, 16, v143
	v_fmac_f32_e32 v144, v163, v163
	v_and_b32_e32 v163, 0xffff0000, v143
	v_fmac_f32_e32 v144, v163, v163
	s_setprio 1
	s_waitcnt lgkmcnt(3)
	v_mfma_f32_32x32x16_bf16 v[112:127], v[140:143], v[146:149], v[112:127]
	s_waitcnt lgkmcnt(2)
	v_mfma_f32_32x32x16_bf16 v[96:111], v[140:143], v[150:153], v[96:111]
	s_waitcnt lgkmcnt(1)
	v_mfma_f32_32x32x16_bf16 v[80:95], v[140:143], v[154:157], v[80:95]
	s_waitcnt lgkmcnt(0)
	v_mfma_f32_32x32x16_bf16 v[64:79], v[140:143], v[158:161], v[64:79]
	v_mfma_f32_32x32x16_bf16 v[48:63], v[136:139], v[146:149], v[48:63]
	v_mfma_f32_32x32x16_bf16 v[32:47], v[136:139], v[150:153], v[32:47]
	v_mfma_f32_32x32x16_bf16 v[16:31], v[136:139], v[154:157], v[16:31]
	v_mfma_f32_32x32x16_bf16 v[0:15], v[136:139], v[158:161], v[0:15]
	s_setprio 0
	ds_read_b128 v[146:149], v145 offset:96
	ds_read_b128 v[140:143], v145 offset:4704
	ds_read_b128 v[150:153], v162 offset:36960
	ds_read_b128 v[154:157], v162 offset:41568
	ds_read_b128 v[158:161], v162 offset:46176
	ds_read_b128 v[162:165], v162 offset:50784
	s_waitcnt lgkmcnt(5)
	v_lshlrev_b32_e32 v145, 16, v146
	v_fmac_f32_e32 v144, v145, v145
	v_and_b32_e32 v145, 0xffff0000, v146
	v_fmac_f32_e32 v144, v145, v145
	v_lshlrev_b32_e32 v145, 16, v147
	v_fmac_f32_e32 v144, v145, v145
	v_and_b32_e32 v145, 0xffff0000, v147
	v_fmac_f32_e32 v144, v145, v145
	v_lshlrev_b32_e32 v145, 16, v148
	v_fmac_f32_e32 v144, v145, v145
	v_and_b32_e32 v145, 0xffff0000, v148
	v_fmac_f32_e32 v144, v145, v145
	v_lshlrev_b32_e32 v145, 16, v149
	v_fmac_f32_e32 v144, v145, v145
	v_and_b32_e32 v145, 0xffff0000, v149
	v_fmac_f32_e32 v144, v145, v145
	s_setprio 1
	s_waitcnt lgkmcnt(3)
	v_mfma_f32_32x32x16_bf16 v[112:127], v[146:149], v[150:153], v[112:127]
	s_waitcnt lgkmcnt(2)
	v_mfma_f32_32x32x16_bf16 v[96:111], v[146:149], v[154:157], v[96:111]
	s_waitcnt lgkmcnt(1)
	v_mfma_f32_32x32x16_bf16 v[80:95], v[146:149], v[158:161], v[80:95]
	s_waitcnt lgkmcnt(0)
	v_mfma_f32_32x32x16_bf16 v[64:79], v[146:149], v[162:165], v[64:79]
	v_mfma_f32_32x32x16_bf16 v[48:63], v[140:143], v[150:153], v[48:63]
	v_mfma_f32_32x32x16_bf16 v[32:47], v[140:143], v[154:157], v[32:47]
	v_mfma_f32_32x32x16_bf16 v[16:31], v[140:143], v[158:161], v[16:31]
	v_mfma_f32_32x32x16_bf16 v[0:15], v[140:143], v[162:165], v[0:15]
	s_setprio 0
	v_and_b32_e32 v145, 64, v207
	v_xor_b32_e32 v147, 32, v207
	v_add_u32_e32 v145, 64, v145
	v_cmp_lt_i32_e32 vcc, v147, v145
	v_mov_b32_e32 v146, v204
	s_nop 0
	v_cndmask_b32_e32 v147, v207, v147, vcc
	s_barrier
; DEV int ltid() { int t = threadIdx.x; asm volatile("" : "+v"(t)); return t; }
; template <int MI>
; DEV void rowss_finish(float (&ss)[MI], int K, char* lds) {
;   using C = GemmCfg<MI>;
;   const int tid = ltid(), lane = tid & 63, wid = tid >> 6, r32 = lane & 31, hi = lane >> 5, wm = wid & 3, wn = wid >> 2;
;   float* rs_l = (float*)(lds + C::RS_OFF);
; #pragma unroll
;   for (int mi = 0; mi < MI; ++mi) {
;     float t = ss[mi] + __shfl_xor(ss[mi], 32);
;     if (wn == 0 && hi == 0) rs_l[wm * 32 * MI + mi * 32 + r32] = rsqrtf(t / (float)K + EPS);
;   }
;   __syncthreads();
; }
	v_lshlrev_b32_e32 v147, 2, v147
	v_and_b32_e32 v148, 0xffffff20, v146
	v_cmp_eq_u32_e64 s[38:39], 0, v148
	ds_bpermute_b32 v148, v147, v144
	v_readlane_b32 s0, v252, 9
	s_nop 1
	v_lshl_add_u32 v146, v146, 2, s0
	s_and_saveexec_b64 s[0:1], s[38:39]
	s_cbranch_execz .LBB0_1009
	s_waitcnt lgkmcnt(0)
	v_add_f32_e32 v144, v144, v148
	s_mov_b32 s5, 0x43c00000
	v_div_scale_f32 v148, s[18:19], s5, s5, v144
	v_rcp_f32_e32 v149, v148
	v_div_scale_f32 v150, vcc, v144, s5, v144
	v_fma_f32 v151, -v148, v149, 1.0
	v_fmac_f32_e32 v149, v151, v149
	v_mul_f32_e32 v151, v150, v149
	v_fma_f32 v152, -v148, v151, v150
	v_fmac_f32_e32 v151, v152, v149
	v_fma_f32 v148, -v148, v151, v150
	v_div_fmas_f32 v148, v148, v149, v151
	v_div_fixup_f32 v144, v148, s5, v144
	v_add_f32_e32 v144, 0x358637bd, v144
	v_mul_f32_e32 v148, 0x4b800000, v144
	v_cmp_gt_f32_e32 vcc, s33, v144
	s_nop 1
	v_cndmask_b32_e32 v144, v144, v148, vcc
	v_rsq_f32_e32 v144, v144
	s_nop 0
	v_mul_f32_e32 v148, 0x45800000, v144
	v_cndmask_b32_e32 v144, v144, v148, vcc
	v_mul_f32_e32 v144, 0x3dd53b94, v144
	ds_write_b32 v146, v144
.LBB0_1009:
	s_or_b64 exec, exec, s[0:1]
	v_lshlrev_b32_e32 v144, 16, v128
	v_fmac_f32_e32 v199, v144, v144
	v_and_b32_e32 v128, 0xffff0000, v128
	v_fmac_f32_e32 v199, v128, v128
	v_lshlrev_b32_e32 v128, 16, v129
	v_fmac_f32_e32 v199, v128, v128
	v_and_b32_e32 v128, 0xffff0000, v129
	v_fmac_f32_e32 v199, v128, v128
	v_lshlrev_b32_e32 v128, 16, v130
	v_fmac_f32_e32 v199, v128, v128
	v_and_b32_e32 v128, 0xffff0000, v130
	v_fmac_f32_e32 v199, v128, v128
	v_lshlrev_b32_e32 v128, 16, v131
	v_fmac_f32_e32 v199, v128, v128
	v_and_b32_e32 v128, 0xffff0000, v131
	v_fmac_f32_e32 v199, v128, v128
	v_lshlrev_b32_e32 v128, 16, v132
	v_fmac_f32_e32 v199, v128, v128
	v_and_b32_e32 v128, 0xffff0000, v132
	v_fmac_f32_e32 v199, v128, v128
	v_lshlrev_b32_e32 v128, 16, v133
	v_fmac_f32_e32 v199, v128, v128
	v_and_b32_e32 v128, 0xffff0000, v133
	v_fmac_f32_e32 v199, v128, v128
	v_lshlrev_b32_e32 v128, 16, v134
	v_fmac_f32_e32 v199, v128, v128
	v_and_b32_e32 v128, 0xffff0000, v134
	v_fmac_f32_e32 v199, v128, v128
	v_lshlrev_b32_e32 v128, 16, v135
	v_fmac_f32_e32 v199, v128, v128
	v_and_b32_e32 v128, 0xffff0000, v135
	v_fmac_f32_e32 v199, v128, v128
	v_lshlrev_b32_e32 v128, 16, v136
	v_fmac_f32_e32 v199, v128, v128
	v_and_b32_e32 v128, 0xffff0000, v136
	v_fmac_f32_e32 v199, v128, v128
	v_lshlrev_b32_e32 v128, 16, v137
	v_fmac_f32_e32 v199, v128, v128
	v_and_b32_e32 v128, 0xffff0000, v137
	v_fmac_f32_e32 v199, v128, v128
	v_lshlrev_b32_e32 v128, 16, v138
	v_fmac_f32_e32 v199, v128, v128
	v_and_b32_e32 v128, 0xffff0000, v138
	v_fmac_f32_e32 v199, v128, v128
	v_lshlrev_b32_e32 v128, 16, v139
	v_fmac_f32_e32 v199, v128, v128
	v_and_b32_e32 v128, 0xffff0000, v139
	v_fmac_f32_e32 v199, v128, v128
	v_lshlrev_b32_e32 v128, 16, v140
	v_fmac_f32_e32 v199, v128, v128
	v_and_b32_e32 v128, 0xffff0000, v140
	v_fmac_f32_e32 v199, v128, v128
	v_lshlrev_b32_e32 v128, 16, v141
	v_fmac_f32_e32 v199, v128, v128
	v_and_b32_e32 v128, 0xffff0000, v141
	v_fmac_f32_e32 v199, v128, v128
	v_lshlrev_b32_e32 v128, 16, v142
	v_fmac_f32_e32 v199, v128, v128
	v_and_b32_e32 v128, 0xffff0000, v142
	v_fmac_f32_e32 v199, v128, v128
	v_lshlrev_b32_e32 v128, 16, v143
	v_fmac_f32_e32 v199, v128, v128
	v_and_b32_e32 v128, 0xffff0000, v143
	v_fmac_f32_e32 v199, v128, v128
	ds_bpermute_b32 v128, v147, v199
	s_and_saveexec_b64 s[0:1], s[38:39]
	s_cbranch_execz .LBB0_1011
	s_waitcnt lgkmcnt(0)
	v_add_f32_e32 v128, v199, v128
	s_mov_b32 s5, 0x43c00000
	v_div_scale_f32 v129, s[18:19], s5, s5, v128
	v_rcp_f32_e32 v130, v129
	v_div_scale_f32 v131, vcc, v128, s5, v128
	v_fma_f32 v132, -v129, v130, 1.0
	v_fmac_f32_e32 v130, v132, v130
	v_mul_f32_e32 v132, v131, v130
	v_fma_f32 v133, -v129, v132, v131
	v_fmac_f32_e32 v132, v133, v130
	v_fma_f32 v129, -v129, v132, v131
	v_div_fmas_f32 v129, v129, v130, v132
	v_div_fixup_f32 v128, v129, s5, v128
	v_add_f32_e32 v128, 0x358637bd, v128
	v_mul_f32_e32 v129, 0x4b800000, v128
	v_cmp_gt_f32_e32 vcc, s33, v128
	s_nop 1
	v_cndmask_b32_e32 v128, v128, v129, vcc
	v_rsq_f32_e32 v128, v128
	s_nop 0
	v_mul_f32_e32 v129, 0x45800000, v128
	v_cndmask_b32_e32 v128, v128, v129, vcc
	v_mul_f32_e32 v128, 0x3dd53b94, v128
	ds_write_b32 v146, v128 offset:128

; __global__ void __launch_bounds__(NTHR) mega(Params p) {
	.amdhsa_kernel _Z4mega6Params
		.amdhsa_group_segment_fixed_size 0
		.amdhsa_private_segment_fixed_size 0
		.amdhsa_kernarg_size 456
		.amdhsa_user_sgpr_count 2
		.amdhsa_user_sgpr_dispatch_ptr 0
		.amdhsa_user_sgpr_queue_ptr 0
		.amdhsa_user_sgpr_kernarg_segment_ptr 1
		.amdhsa_user_sgpr_dispatch_id 0
		.amdhsa_user_sgpr_kernarg_preload_length 0
		.amdhsa_user_sgpr_kernarg_preload_offset 0
		.amdhsa_user_sgpr_private_segment_size 0
		.amdhsa_uses_dynamic_stack 0
		.amdhsa_enable_private_segment 0
		.amdhsa_system_sgpr_workgroup_id_x 1
		.amdhsa_system_sgpr_workgroup_id_y 0
		.amdhsa_system_sgpr_workgroup_id_z 0
		.amdhsa_system_sgpr_workgroup_info 0
		.amdhsa_system_vgpr_workitem_id 2
		.amdhsa_next_free_vgpr 255
		.amdhsa_next_free_sgpr 102
		.amdhsa_accum_offset 256
		.amdhsa_reserve_vcc 1
		.amdhsa_float_round_mode_32 0
		.amdhsa_float_round_mode_16_64 0
		.amdhsa_float_denorm_mode_32 3
		.amdhsa_float_denorm_mode_16_64 3
		.amdhsa_dx10_clamp 1
		.amdhsa_ieee_mode 1
		.amdhsa_fp16_overflow 0
		.amdhsa_tg_split 0
		.amdhsa_exception_fp_ieee_invalid_op 0
		.amdhsa_exception_fp_denorm_src 0
		.amdhsa_exception_fp_ieee_div_zero 0
		.amdhsa_exception_fp_ieee_overflow 0
		.amdhsa_exception_fp_ieee_underflow 0
		.amdhsa_exception_fp_ieee_inexact 0
		.amdhsa_exception_int_div_zero 0
	.end_amdhsa_kernel

; __global__ void __launch_bounds__(NTHR) mega(Params p) {
; __global__ void __launch_bounds__(NTHR) phase_k(Params p, int grp, int l, int ph) {
amdhsa.kernels:
  - .agpr_count:     0
    .args:
      - .offset:         0
        .size:           200
        .value_kind:     by_value
      - .offset:         200
        .size:           4
        .value_kind:     hidden_block_count_x
      - .offset:         204
        .size:           4
        .value_kind:     hidden_block_count_y
      - .offset:         208
        .size:           4
        .value_kind:     hidden_block_count_z
      - .offset:         212
        .size:           2
        .value_kind:     hidden_group_size_x
      - .offset:         214
        .size:           2
        .value_kind:     hidden_group_size_y
      - .offset:         216
        .size:           2
        .value_kind:     hidden_group_size_z
      - .offset:         218
        .size:           2
        .value_kind:     hidden_remainder_x
      - .offset:         220
        .size:           2
        .value_kind:     hidden_remainder_y
      - .offset:         222
        .size:           2
        .value_kind:     hidden_remainder_z
      - .offset:         240
        .size:           8
        .value_kind:     hidden_global_offset_x
      - .offset:         248
        .size:           8
        .value_kind:     hidden_global_offset_y
      - .offset:         256
        .size:           8
        .value_kind:     hidden_global_offset_z
      - .offset:         264
        .size:           2
        .value_kind:     hidden_grid_dims
      - .offset:         288
        .size:           8
        .value_kind:     hidden_multigrid_sync_arg
      - .offset:         320
        .size:           4
        .value_kind:     hidden_dynamic_lds_size
    .group_segment_fixed_size: 0
    .kernarg_segment_align: 8
    .kernarg_segment_size: 456
    .language:       OpenCL C
    .language_version:
      - 2
      - 0
    .max_flat_workgroup_size: 512
    .name:           _Z4mega6Params
    .private_segment_fixed_size: 0
    .sgpr_count:     108
    .sgpr_spill_count: 475
    .symbol:         _Z4mega6Params.kd
    .uniform_work_group_size: 1
    .uses_dynamic_stack: false
    .vgpr_count:     255
    .vgpr_spill_count: 0
    .wavefront_size: 64
  - .agpr_count:     0
    .args:
      - .offset:         0
        .size:           200
        .value_kind:     by_value
      - .offset:         200
        .size:           4
        .value_kind:     by_value
      - .offset:         204
        .size:           4
        .value_kind:     by_value
      - .offset:         208
        .size:           4
        .value_kind:     by_value
      - .offset:         216
        .size:           4
        .value_kind:     hidden_block_count_x
      - .offset:         220
        .size:           4
        .value_kind:     hidden_block_count_y
      - .offset:         224
        .size:           4
        .value_kind:     hidden_block_count_z
      - .offset:         228
        .size:           2
        .value_kind:     hidden_group_size_x
      - .offset:         230
        .size:           2
        .value_kind:     hidden_group_size_y
      - .offset:         232
        .size:           2
        .value_kind:     hidden_group_size_z
      - .offset:         234
        .size:           2
        .value_kind:     hidden_remainder_x
      - .offset:         236
        .size:           2
        .value_kind:     hidden_remainder_y
      - .offset:         238
        .size:           2
        .value_kind:     hidden_remainder_z
      - .offset:         256
        .size:           8
        .value_kind:     hidden_global_offset_x
      - .offset:         264
        .size:           8
        .value_kind:     hidden_global_offset_y
      - .offset:         272
        .size:           8
        .value_kind:     hidden_global_offset_z
      - .offset:         280
        .size:           2
        .value_kind:     hidden_grid_dims
      - .offset:         336
        .size:           4
        .value_kind:     hidden_dynamic_lds_size
    .group_segment_fixed_size: 0
    .kernarg_segment_align: 8
    .kernarg_segment_size: 472
    .language:       OpenCL C
    .language_version:
      - 2
      - 0
    .max_flat_workgroup_size: 512
    .name:           _Z7phase_k6Paramsiii
    .private_segment_fixed_size: 0
    .sgpr_count:     104
    .sgpr_spill_count: 96
    .symbol:         _Z7phase_k6Paramsiii.kd
    .uniform_work_group_size: 1
    .uses_dynamic_stack: false
    .vgpr_count:     256
    .vgpr_spill_count: 0
    .wavefront_size: 64
